# k-loops: per-step priority flips replaced by one static s_setprio 1 for odd hardware wave slots (younger co-resident block)
# speedup vs baseline: 1.1581x; 1.0152x over previous
.LBB0_199:
	s_or_b64 exec, exec, s[26:27]
	s_lshl_b64 s[40:41], s[0:1], 11
	s_add_u32 s28, s66, s40
	s_addc_u32 s29, s67, s41
	s_mul_i32 s40, s4, 0xc0
	s_ashr_i32 s41, s40, 31
	s_lshl_b64 s[46:47], s[40:41], 11
	s_add_u32 s36, s80, s46
	s_addc_u32 s37, s81, s47
	v_lshrrev_b32_e32 v196, 3, v197
	v_and_b32_e32 v198, 7, v197
	v_lshlrev_b32_e32 v138, 11, v196
	v_lshl_or_b32 v138, v198, 4, v138
	v_add_u32_e32 v139, 0x10000, v138
	v_add_u32_e32 v140, 0x20000, v138
	v_add_u32_e32 v141, 0x30000, v138
	v_add_u32_e32 v142, 0x40000, v138
	v_add_u32_e32 v143, 0x50000, v138
	global_load_dwordx4 v[96:99], v138, s[28:29]
	global_load_dwordx4 v[100:103], v139, s[28:29]
	global_load_dwordx4 v[104:107], v140, s[28:29]
	global_load_dwordx4 v[108:111], v141, s[28:29]
	global_load_dwordx4 v[112:115], v138, s[36:37]
	global_load_dwordx4 v[116:119], v139, s[36:37]
	global_load_dwordx4 v[120:123], v140, s[36:37]
	global_load_dwordx4 v[124:127], v141, s[36:37]
	global_load_dwordx4 v[128:131], v142, s[36:37]
	global_load_dwordx4 v[132:135], v143, s[36:37]
	s_add_u32 s28, s28, 0x80
	s_addc_u32 s29, s29, 0
	s_add_u32 s36, s36, 0x80
	s_addc_u32 s37, s37, 0
	s_mul_i32 s26, s4, 0xc0
	s_ashr_i32 s27, s26, 31
	v_bfe_u32 v217, v197, 5, 2
	v_and_b32_e32 v218, 3, v198
	v_xor_b32_e32 v218, v218, v217
	v_lshlrev_b32_e32 v218, 4, v218
	v_lshl_or_b32 v250, v196, 6, v218
	v_lshrrev_b32_e32 v217, 2, v198
	v_lshlrev_b32_e32 v218, 6, v217
	v_xor_b32_e32 v250, v250, v218
	v_mul_u32_u24_e32 v217, 0x5000, v217
	v_add_u32_e32 v250, v250, v217
	v_and_b32_e32 v196, 31, v197
	v_bfe_u32 v198, v197, 5, 1
	v_bfe_u32 v217, v197, 2, 2
	v_xor_b32_e32 v218, v198, v217
	v_xor_b32_e32 v221, 2, v218
	v_lshrrev_b32_e32 v198, 7, v197
	v_lshl_or_b32 v198, v198, 6, v196
	v_lshlrev_b32_e32 v198, 6, v198
	v_lshl_or_b32 v242, v218, 4, v198
	v_lshl_or_b32 v243, v221, 4, v198
	v_bfe_u32 v198, v197, 6, 1
	v_mul_u32_u24_e32 v198, 96, v198
	v_add_u32_e32 v198, v198, v196
	v_lshlrev_b32_e32 v198, 6, v198
	v_add_u32_e32 v198, 0x2000, v198
	v_lshl_or_b32 v244, v218, 4, v198
	v_lshl_or_b32 v245, v221, 4, v198
	v_mov_b64_e32 v[0:1], 0
	v_mov_b64_e32 v[2:3], 0
	v_mov_b64_e32 v[4:5], 0
	v_mov_b64_e32 v[6:7], 0
	v_mov_b64_e32 v[8:9], 0
	v_mov_b64_e32 v[10:11], 0
	v_mov_b64_e32 v[12:13], 0
	v_mov_b64_e32 v[14:15], 0
	v_mov_b64_e32 v[16:17], 0
	v_mov_b64_e32 v[18:19], 0
	v_mov_b64_e32 v[20:21], 0
	v_mov_b64_e32 v[22:23], 0
	v_mov_b64_e32 v[24:25], 0
	v_mov_b64_e32 v[26:27], 0
	v_mov_b64_e32 v[28:29], 0
	v_mov_b64_e32 v[30:31], 0
	v_mov_b64_e32 v[32:33], 0
	v_mov_b64_e32 v[34:35], 0
	v_mov_b64_e32 v[36:37], 0
	v_mov_b64_e32 v[38:39], 0
	v_mov_b64_e32 v[40:41], 0
	v_mov_b64_e32 v[42:43], 0
	v_mov_b64_e32 v[44:45], 0
	v_mov_b64_e32 v[46:47], 0
	v_mov_b64_e32 v[48:49], 0
	v_mov_b64_e32 v[50:51], 0
	v_mov_b64_e32 v[52:53], 0
	v_mov_b64_e32 v[54:55], 0
	v_mov_b64_e32 v[56:57], 0
	v_mov_b64_e32 v[58:59], 0
	v_mov_b64_e32 v[60:61], 0
	v_mov_b64_e32 v[62:63], 0
	v_mov_b64_e32 v[64:65], 0
	v_mov_b64_e32 v[66:67], 0
	v_mov_b64_e32 v[68:69], 0
	v_mov_b64_e32 v[70:71], 0
	v_mov_b64_e32 v[72:73], 0
	v_mov_b64_e32 v[74:75], 0
	v_mov_b64_e32 v[76:77], 0
	v_mov_b64_e32 v[78:79], 0
	v_mov_b64_e32 v[80:81], 0
	v_mov_b64_e32 v[82:83], 0
	v_mov_b64_e32 v[84:85], 0
	v_mov_b64_e32 v[86:87], 0
	v_mov_b64_e32 v[88:89], 0
	v_mov_b64_e32 v[90:91], 0
	v_mov_b64_e32 v[92:93], 0
	v_mov_b64_e32 v[94:95], 0
	s_mov_b32 s38, 0
	s_mov_b32 s39, 0x5000
	s_mov_b32 s5, 0
	s_waitcnt vmcnt(9)
	ds_write_b128 v250, v[96:99]
	s_waitcnt vmcnt(8)
	ds_write_b128 v250, v[100:103] offset:2048
	s_waitcnt vmcnt(7)
	ds_write_b128 v250, v[104:107] offset:4096
	s_waitcnt vmcnt(6)
	ds_write_b128 v250, v[108:111] offset:6144
	s_waitcnt vmcnt(5)
	ds_write_b128 v250, v[112:115] offset:8192
	s_waitcnt vmcnt(4)
	ds_write_b128 v250, v[116:119] offset:10240
	s_waitcnt vmcnt(3)
	ds_write_b128 v250, v[120:123] offset:12288
	s_waitcnt vmcnt(2)
	ds_write_b128 v250, v[124:127] offset:14336
	s_waitcnt vmcnt(1)
	ds_write_b128 v250, v[128:131] offset:16384
	s_waitcnt vmcnt(0)
	ds_write_b128 v250, v[132:135] offset:18432
	v_subrev_u32_e32 v196, 0x5000, v250
	v_add_u32_e32 v198, 0xa000, v250
	v_min_u32_e32 v250, v196, v198
	s_waitcnt lgkmcnt(0)
	s_barrier
	s_getreg_b32 s40, hwreg(HW_REG_HW_ID, 0, 4)
	s_bitcmp1_b32 s40, 0
	s_cbranch_scc0 .Lg1_noraise
	s_setprio 1
.Lg1_noraise:
.Lg1_loop:
	v_add_u32_e32 v246, s38, v242
	v_add_u32_e32 v247, s38, v243
	v_add_u32_e32 v248, s38, v244
	v_add_u32_e32 v249, s38, v245
	ds_read_b128 v[144:147], v246
	ds_read_b128 v[148:151], v246 offset:2048
	ds_read_b128 v[160:163], v248
	ds_read_b128 v[164:167], v248 offset:2048
	ds_read_b128 v[168:171], v248 offset:4096
	s_waitcnt lgkmcnt(2)
	v_mfma_f32_32x32x16_bf16 v[80:95], v[144:147], v[160:163], v[80:95]
	global_load_dwordx4 v[96:99], v138, s[28:29]
	ds_read_b128 v[152:155], v247
	v_mfma_f32_32x32x16_bf16 v[32:47], v[148:151], v[160:163], v[32:47]
	global_load_dwordx4 v[100:103], v139, s[28:29]
	ds_read_b128 v[156:159], v247 offset:2048
	s_waitcnt lgkmcnt(3)
	v_mfma_f32_32x32x16_bf16 v[64:79], v[144:147], v[164:167], v[64:79]
	global_load_dwordx4 v[104:107], v140, s[28:29]
	ds_read_b128 v[172:175], v249
	v_mfma_f32_32x32x16_bf16 v[16:31], v[148:151], v[164:167], v[16:31]
	global_load_dwordx4 v[108:111], v141, s[28:29]
	ds_read_b128 v[176:179], v249 offset:2048
	s_waitcnt lgkmcnt(4)
	v_mfma_f32_32x32x16_bf16 v[48:63], v[144:147], v[168:171], v[48:63]
	global_load_dwordx4 v[112:115], v138, s[36:37]
	ds_read_b128 v[180:183], v249 offset:4096
	v_mfma_f32_32x32x16_bf16 v[0:15], v[148:151], v[168:171], v[0:15]
	global_load_dwordx4 v[116:119], v139, s[36:37]
	v_xad_u32 v246, v242, 64, s39
	v_xad_u32 v248, v244, 64, s39
	s_waitcnt lgkmcnt(2)
	v_mfma_f32_32x32x16_bf16 v[80:95], v[152:155], v[172:175], v[80:95]
	global_load_dwordx4 v[120:123], v140, s[36:37]
	ds_read_b128 v[144:147], v246
	v_mfma_f32_32x32x16_bf16 v[32:47], v[156:159], v[172:175], v[32:47]
	global_load_dwordx4 v[124:127], v141, s[36:37]
	ds_read_b128 v[148:151], v246 offset:2048
	s_waitcnt lgkmcnt(3)
	v_mfma_f32_32x32x16_bf16 v[64:79], v[152:155], v[176:179], v[64:79]
	global_load_dwordx4 v[128:131], v142, s[36:37]
	ds_read_b128 v[160:163], v248
	v_mfma_f32_32x32x16_bf16 v[16:31], v[156:159], v[176:179], v[16:31]
	global_load_dwordx4 v[132:135], v143, s[36:37]
	ds_read_b128 v[164:167], v248 offset:2048
	s_waitcnt lgkmcnt(4)
	v_mfma_f32_32x32x16_bf16 v[48:63], v[152:155], v[180:183], v[48:63]
	ds_read_b128 v[168:171], v248 offset:4096
	v_mfma_f32_32x32x16_bf16 v[0:15], v[156:159], v[180:183], v[0:15]
	s_barrier
	v_xad_u32 v247, v243, 64, s39
	v_xad_u32 v249, v245, 64, s39
	s_waitcnt lgkmcnt(2)
	v_mfma_f32_32x32x16_bf16 v[80:95], v[144:147], v[160:163], v[80:95]
	ds_read_b128 v[152:155], v247
	v_mfma_f32_32x32x16_bf16 v[32:47], v[148:151], v[160:163], v[32:47]
	ds_read_b128 v[156:159], v247 offset:2048
	s_waitcnt lgkmcnt(3)
	v_mfma_f32_32x32x16_bf16 v[64:79], v[144:147], v[164:167], v[64:79]
	ds_read_b128 v[172:175], v249
	s_waitcnt vmcnt(9)
	ds_write_b128 v250, v[96:99]
	v_mfma_f32_32x32x16_bf16 v[16:31], v[148:151], v[164:167], v[16:31]
	ds_read_b128 v[176:179], v249 offset:2048
	s_waitcnt vmcnt(8)
	ds_write_b128 v250, v[100:103] offset:2048
	s_waitcnt lgkmcnt(6)
	v_mfma_f32_32x32x16_bf16 v[48:63], v[144:147], v[168:171], v[48:63]
	ds_read_b128 v[180:183], v249 offset:4096
	s_waitcnt vmcnt(7)
	ds_write_b128 v250, v[104:107] offset:4096
	v_mfma_f32_32x32x16_bf16 v[0:15], v[148:151], v[168:171], v[0:15]
	s_waitcnt vmcnt(6)
	ds_write_b128 v250, v[108:111] offset:6144
	s_waitcnt lgkmcnt(6)
	v_mfma_f32_32x32x16_bf16 v[80:95], v[152:155], v[172:175], v[80:95]
	s_waitcnt vmcnt(5)
	ds_write_b128 v250, v[112:115] offset:8192
	v_mfma_f32_32x32x16_bf16 v[32:47], v[156:159], v[172:175], v[32:47]
	s_waitcnt vmcnt(4)
	ds_write_b128 v250, v[116:119] offset:10240
	s_waitcnt lgkmcnt(6)
	v_mfma_f32_32x32x16_bf16 v[64:79], v[152:155], v[176:179], v[64:79]
	s_waitcnt vmcnt(3)
	ds_write_b128 v250, v[120:123] offset:12288
	v_mfma_f32_32x32x16_bf16 v[16:31], v[156:159], v[176:179], v[16:31]
	s_waitcnt vmcnt(2)
	ds_write_b128 v250, v[124:127] offset:14336
	s_waitcnt lgkmcnt(6)
	v_mfma_f32_32x32x16_bf16 v[48:63], v[152:155], v[180:183], v[48:63]
	s_waitcnt vmcnt(1)
	ds_write_b128 v250, v[128:131] offset:16384
	v_mfma_f32_32x32x16_bf16 v[0:15], v[156:159], v[180:183], v[0:15]
	s_waitcnt vmcnt(0)
	ds_write_b128 v250, v[132:135] offset:18432
	s_add_u32 s28, s28, 0x80
	s_addc_u32 s29, s29, 0
	s_add_u32 s36, s36, 0x80
	s_addc_u32 s37, s37, 0
	s_sub_i32 s38, s38, 0x5000
	s_cmp_lt_i32 s38, 0
	s_cselect_b32 s40, 0xf000, 0
	s_add_i32 s38, s38, s40
	s_sub_i32 s39, s39, 0x5000
	s_cmp_lt_i32 s39, 0
	s_cselect_b32 s40, 0xf000, 0
	s_add_i32 s39, s39, s40
	v_subrev_u32_e32 v196, 0x5000, v250
	v_add_u32_e32 v198, 0xa000, v250
	v_min_u32_e32 v250, v196, v198
	s_add_i32 s5, s5, 1
	s_cmp_lt_u32 s5, 15
	s_waitcnt lgkmcnt(0)
	s_barrier
	s_cbranch_scc1 .Lg1_loop
	v_add_u32_e32 v246, s38, v242
	v_add_u32_e32 v247, s38, v243
	v_add_u32_e32 v248, s38, v244
	v_add_u32_e32 v249, s38, v245
	ds_read_b128 v[144:147], v246
	ds_read_b128 v[148:151], v246 offset:2048
	ds_read_b128 v[160:163], v248
	ds_read_b128 v[164:167], v248 offset:2048
	ds_read_b128 v[168:171], v248 offset:4096
	s_waitcnt lgkmcnt(2)
	v_mfma_f32_32x32x16_bf16 v[80:95], v[144:147], v[160:163], v[80:95]
	ds_read_b128 v[152:155], v247
	v_mfma_f32_32x32x16_bf16 v[32:47], v[148:151], v[160:163], v[32:47]
	ds_read_b128 v[156:159], v247 offset:2048
	s_waitcnt lgkmcnt(3)
	v_mfma_f32_32x32x16_bf16 v[64:79], v[144:147], v[164:167], v[64:79]
	ds_read_b128 v[172:175], v249
	v_mfma_f32_32x32x16_bf16 v[16:31], v[148:151], v[164:167], v[16:31]
	ds_read_b128 v[176:179], v249 offset:2048
	s_waitcnt lgkmcnt(4)
	v_mfma_f32_32x32x16_bf16 v[48:63], v[144:147], v[168:171], v[48:63]
	ds_read_b128 v[180:183], v249 offset:4096
	v_mfma_f32_32x32x16_bf16 v[0:15], v[148:151], v[168:171], v[0:15]
	v_xad_u32 v246, v242, 64, s39
	v_xad_u32 v248, v244, 64, s39
	s_waitcnt lgkmcnt(2)
	v_mfma_f32_32x32x16_bf16 v[80:95], v[152:155], v[172:175], v[80:95]
	ds_read_b128 v[144:147], v246
	v_mfma_f32_32x32x16_bf16 v[32:47], v[156:159], v[172:175], v[32:47]
	ds_read_b128 v[148:151], v246 offset:2048
	s_waitcnt lgkmcnt(3)
	v_mfma_f32_32x32x16_bf16 v[64:79], v[152:155], v[176:179], v[64:79]
	ds_read_b128 v[160:163], v248
	v_mfma_f32_32x32x16_bf16 v[16:31], v[156:159], v[176:179], v[16:31]
	ds_read_b128 v[164:167], v248 offset:2048
	s_waitcnt lgkmcnt(4)
	v_mfma_f32_32x32x16_bf16 v[48:63], v[152:155], v[180:183], v[48:63]
	ds_read_b128 v[168:171], v248 offset:4096
	v_mfma_f32_32x32x16_bf16 v[0:15], v[156:159], v[180:183], v[0:15]
	v_xad_u32 v247, v243, 64, s39
	v_xad_u32 v249, v245, 64, s39
	s_waitcnt lgkmcnt(2)
	v_mfma_f32_32x32x16_bf16 v[80:95], v[144:147], v[160:163], v[80:95]
	ds_read_b128 v[152:155], v247
	v_mfma_f32_32x32x16_bf16 v[32:47], v[148:151], v[160:163], v[32:47]
	ds_read_b128 v[156:159], v247 offset:2048
	s_waitcnt lgkmcnt(3)
	v_mfma_f32_32x32x16_bf16 v[64:79], v[144:147], v[164:167], v[64:79]
	ds_read_b128 v[172:175], v249
	v_mfma_f32_32x32x16_bf16 v[16:31], v[148:151], v[164:167], v[16:31]
	ds_read_b128 v[176:179], v249 offset:2048
	s_waitcnt lgkmcnt(4)
	v_mfma_f32_32x32x16_bf16 v[48:63], v[144:147], v[168:171], v[48:63]
	ds_read_b128 v[180:183], v249 offset:4096
	v_mfma_f32_32x32x16_bf16 v[0:15], v[148:151], v[168:171], v[0:15]
	s_waitcnt lgkmcnt(2)
	v_mfma_f32_32x32x16_bf16 v[80:95], v[152:155], v[172:175], v[80:95]
	v_mfma_f32_32x32x16_bf16 v[32:47], v[156:159], v[172:175], v[32:47]
	s_waitcnt lgkmcnt(1)
	v_mfma_f32_32x32x16_bf16 v[64:79], v[152:155], v[176:179], v[64:79]
	v_mfma_f32_32x32x16_bf16 v[16:31], v[156:159], v[176:179], v[16:31]
	s_waitcnt lgkmcnt(0)
	v_mfma_f32_32x32x16_bf16 v[48:63], v[152:155], v[180:183], v[48:63]
	v_mfma_f32_32x32x16_bf16 v[0:15], v[156:159], v[180:183], v[0:15]
	s_setprio 0
	s_nop 7
	s_nop 7

.LBB0_406:
	s_lshl_b32 s6, s5, 5
	s_and_b32 s26, s6, 0xffffff80
	s_lshl_b32 s6, s5, 8
	s_ashr_i32 s27, s26, 31
	s_and_b32 s68, s6, 0x300
	s_lshl_b64 s[8:9], s[26:27], 11
	v_readlane_b32 s7, v252, 50
	v_readlane_b32 s0, v252, 51
	s_nop 1
	s_add_u32 s28, s7, s8
	s_addc_u32 s29, s0, s9
	s_lshl_b32 s7, s68, 11
	s_add_u32 s38, s80, s7
	s_addc_u32 s39, s81, 0
	v_lshrrev_b32_e32 v196, 3, v197
	v_and_b32_e32 v198, 7, v197
	v_lshlrev_b32_e32 v176, 11, v196
	v_lshl_or_b32 v176, v198, 4, v176
	v_add_u32_e32 v177, 0x10000, v176
	v_add_u32_e32 v178, 0x20000, v176
	v_add_u32_e32 v179, 0x30000, v176
	v_add_u32_e32 v180, 0x40000, v176
	v_add_u32_e32 v181, 0x50000, v176
	v_add_u32_e32 v182, 0x60000, v176
	v_add_u32_e32 v184, 0x70000, v176
	global_load_dwordx4 v[128:131], v176, s[28:29]
	global_load_dwordx4 v[132:135], v177, s[28:29]
	global_load_dwordx4 v[136:139], v178, s[28:29]
	global_load_dwordx4 v[140:143], v179, s[28:29]
	global_load_dwordx4 v[144:147], v176, s[38:39]
	global_load_dwordx4 v[148:151], v177, s[38:39]
	global_load_dwordx4 v[152:155], v178, s[38:39]
	global_load_dwordx4 v[156:159], v179, s[38:39]
	global_load_dwordx4 v[160:163], v180, s[38:39]
	global_load_dwordx4 v[164:167], v181, s[38:39]
	global_load_dwordx4 v[168:171], v182, s[38:39]
	global_load_dwordx4 v[172:175], v184, s[38:39]
	s_add_u32 s28, s28, 0x80
	s_addc_u32 s29, s29, 0
	s_add_u32 s38, s38, 0x80
	s_addc_u32 s39, s39, 0
	v_bfe_u32 v217, v197, 5, 2
	v_and_b32_e32 v218, 3, v198
	v_xor_b32_e32 v218, v218, v217
	v_lshlrev_b32_e32 v218, 4, v218
	v_lshl_or_b32 v185, v196, 6, v218
	v_lshrrev_b32_e32 v217, 2, v198
	v_lshlrev_b32_e32 v218, 6, v217
	v_xor_b32_e32 v185, v185, v218
	v_mul_u32_u24_e32 v217, 0x6000, v217
	v_add_u32_e32 v185, v185, v217
	v_and_b32_e32 v196, 31, v197
	v_bfe_u32 v198, v197, 5, 1
	v_bfe_u32 v217, v197, 2, 2
	v_xor_b32_e32 v218, v198, v217
	v_xor_b32_e32 v221, 2, v218
	v_lshrrev_b32_e32 v198, 7, v197
	v_lshl_or_b32 v198, v198, 6, v196
	v_lshlrev_b32_e32 v198, 6, v198
	v_lshl_or_b32 v186, v218, 4, v198
	v_lshl_or_b32 v187, v221, 4, v198
	v_bfe_u32 v198, v197, 6, 1
	v_mul_u32_u24_e32 v198, 128, v198
	v_add_u32_e32 v198, v198, v196
	v_lshlrev_b32_e32 v198, 6, v198
	v_add_u32_e32 v198, 0x2000, v198
	v_lshl_or_b32 v188, v218, 4, v198
	v_lshl_or_b32 v189, v221, 4, v198
	v_mov_b64_e32 v[0:1], 0
	v_mov_b64_e32 v[2:3], 0
	v_mov_b64_e32 v[4:5], 0
	v_mov_b64_e32 v[6:7], 0
	v_mov_b64_e32 v[8:9], 0
	v_mov_b64_e32 v[10:11], 0
	v_mov_b64_e32 v[12:13], 0
	v_mov_b64_e32 v[14:15], 0
	v_mov_b64_e32 v[16:17], 0
	v_mov_b64_e32 v[18:19], 0
	v_mov_b64_e32 v[20:21], 0
	v_mov_b64_e32 v[22:23], 0
	v_mov_b64_e32 v[24:25], 0
	v_mov_b64_e32 v[26:27], 0
	v_mov_b64_e32 v[28:29], 0
	v_mov_b64_e32 v[30:31], 0
	v_mov_b64_e32 v[32:33], 0
	v_mov_b64_e32 v[34:35], 0
	v_mov_b64_e32 v[36:37], 0
	v_mov_b64_e32 v[38:39], 0
	v_mov_b64_e32 v[40:41], 0
	v_mov_b64_e32 v[42:43], 0
	v_mov_b64_e32 v[44:45], 0
	v_mov_b64_e32 v[46:47], 0
	v_mov_b64_e32 v[48:49], 0
	v_mov_b64_e32 v[50:51], 0
	v_mov_b64_e32 v[52:53], 0
	v_mov_b64_e32 v[54:55], 0
	v_mov_b64_e32 v[56:57], 0
	v_mov_b64_e32 v[58:59], 0
	v_mov_b64_e32 v[60:61], 0
	v_mov_b64_e32 v[62:63], 0
	v_mov_b64_e32 v[64:65], 0
	v_mov_b64_e32 v[66:67], 0
	v_mov_b64_e32 v[68:69], 0
	v_mov_b64_e32 v[70:71], 0
	v_mov_b64_e32 v[72:73], 0
	v_mov_b64_e32 v[74:75], 0
	v_mov_b64_e32 v[76:77], 0
	v_mov_b64_e32 v[78:79], 0
	v_mov_b64_e32 v[80:81], 0
	v_mov_b64_e32 v[82:83], 0
	v_mov_b64_e32 v[84:85], 0
	v_mov_b64_e32 v[86:87], 0
	v_mov_b64_e32 v[88:89], 0
	v_mov_b64_e32 v[90:91], 0
	v_mov_b64_e32 v[92:93], 0
	v_mov_b64_e32 v[94:95], 0
	v_mov_b64_e32 v[96:97], 0
	v_mov_b64_e32 v[98:99], 0
	v_mov_b64_e32 v[100:101], 0
	v_mov_b64_e32 v[102:103], 0
	v_mov_b64_e32 v[104:105], 0
	v_mov_b64_e32 v[106:107], 0
	v_mov_b64_e32 v[108:109], 0
	v_mov_b64_e32 v[110:111], 0
	v_mov_b64_e32 v[112:113], 0
	v_mov_b64_e32 v[114:115], 0
	v_mov_b64_e32 v[116:117], 0
	v_mov_b64_e32 v[118:119], 0
	v_mov_b64_e32 v[120:121], 0
	v_mov_b64_e32 v[122:123], 0
	v_mov_b64_e32 v[124:125], 0
	v_mov_b64_e32 v[126:127], 0
	s_mov_b32 s40, 0
	s_mov_b32 s41, 0x6000
	s_mov_b32 s7, 0
	s_waitcnt vmcnt(11)
	ds_write_b128 v185, v[128:131]
	s_waitcnt vmcnt(10)
	ds_write_b128 v185, v[132:135] offset:2048
	s_waitcnt vmcnt(9)
	ds_write_b128 v185, v[136:139] offset:4096
	s_waitcnt vmcnt(8)
	ds_write_b128 v185, v[140:143] offset:6144
	s_waitcnt vmcnt(7)
	ds_write_b128 v185, v[144:147] offset:8192
	s_waitcnt vmcnt(6)
	ds_write_b128 v185, v[148:151] offset:10240
	s_waitcnt vmcnt(5)
	ds_write_b128 v185, v[152:155] offset:12288
	s_waitcnt vmcnt(4)
	ds_write_b128 v185, v[156:159] offset:14336
	s_waitcnt vmcnt(3)
	ds_write_b128 v185, v[160:163] offset:16384
	s_waitcnt vmcnt(2)
	ds_write_b128 v185, v[164:167] offset:18432
	s_waitcnt vmcnt(1)
	ds_write_b128 v185, v[168:171] offset:20480
	s_waitcnt vmcnt(0)
	ds_write_b128 v185, v[172:175] offset:22528
	v_subrev_u32_e32 v196, 0x6000, v185
	v_add_u32_e32 v198, 0xc000, v185
	v_min_u32_e32 v185, v196, v198
	s_waitcnt lgkmcnt(0)
	s_barrier
	s_getreg_b32 s42, hwreg(HW_REG_HW_ID, 0, 4)
	s_bitcmp1_b32 s42, 0
	s_cbranch_scc0 .Lg4_noraise
	s_setprio 1
.Lg4_noraise:
.Lg4_loop:
	v_add_u32_e32 v190, s40, v186
	v_add_u32_e32 v191, s40, v187
	v_add_u32_e32 v250, s40, v188
	v_add_u32_e32 v251, s40, v189
	ds_read_b128 v[200:203], v190
	ds_read_b128 v[204:207], v190 offset:2048
	ds_read_b128 v[222:225], v250
	ds_read_b128 v[226:229], v250 offset:2048
	ds_read_b128 v[230:233], v250 offset:4096
	ds_read_b128 v[234:237], v250 offset:6144
	s_waitcnt lgkmcnt(3)
	v_mfma_f32_32x32x16_bf16 v[112:127], v[200:203], v[222:225], v[112:127]
	global_load_dwordx4 v[128:131], v176, s[28:29]
	ds_read_b128 v[208:211], v191
	v_mfma_f32_32x32x16_bf16 v[48:63], v[204:207], v[222:225], v[48:63]
	global_load_dwordx4 v[132:135], v177, s[28:29]
	ds_read_b128 v[212:215], v191 offset:2048
	s_waitcnt lgkmcnt(4)
	v_mfma_f32_32x32x16_bf16 v[96:111], v[200:203], v[226:229], v[96:111]
	global_load_dwordx4 v[136:139], v178, s[28:29]
	ds_read_b128 v[238:241], v251
	v_mfma_f32_32x32x16_bf16 v[32:47], v[204:207], v[226:229], v[32:47]
	global_load_dwordx4 v[140:143], v179, s[28:29]
	ds_read_b128 v[242:245], v251 offset:2048
	s_waitcnt lgkmcnt(5)
	v_mfma_f32_32x32x16_bf16 v[80:95], v[200:203], v[230:233], v[80:95]
	global_load_dwordx4 v[144:147], v176, s[38:39]
	ds_read_b128 v[246:249], v251 offset:4096
	v_mfma_f32_32x32x16_bf16 v[16:31], v[204:207], v[230:233], v[16:31]
	global_load_dwordx4 v[148:151], v177, s[38:39]
	ds_read_b128 v[192:195], v251 offset:6144
	s_waitcnt lgkmcnt(6)
	v_mfma_f32_32x32x16_bf16 v[64:79], v[200:203], v[234:237], v[64:79]
	global_load_dwordx4 v[152:155], v178, s[38:39]
	v_mfma_f32_32x32x16_bf16 v[0:15], v[204:207], v[234:237], v[0:15]
	global_load_dwordx4 v[156:159], v179, s[38:39]
	v_xad_u32 v190, v186, 64, s41
	v_xad_u32 v250, v188, 64, s41
	s_waitcnt lgkmcnt(3)
	v_mfma_f32_32x32x16_bf16 v[112:127], v[208:211], v[238:241], v[112:127]
	global_load_dwordx4 v[160:163], v180, s[38:39]
	ds_read_b128 v[200:203], v190
	v_mfma_f32_32x32x16_bf16 v[48:63], v[212:215], v[238:241], v[48:63]
	global_load_dwordx4 v[164:167], v181, s[38:39]
	ds_read_b128 v[204:207], v190 offset:2048
	s_waitcnt lgkmcnt(4)
	v_mfma_f32_32x32x16_bf16 v[96:111], v[208:211], v[242:245], v[96:111]
	global_load_dwordx4 v[168:171], v182, s[38:39]
	ds_read_b128 v[222:225], v250
	v_mfma_f32_32x32x16_bf16 v[32:47], v[212:215], v[242:245], v[32:47]
	global_load_dwordx4 v[172:175], v184, s[38:39]
	ds_read_b128 v[226:229], v250 offset:2048
	s_waitcnt lgkmcnt(5)
	v_mfma_f32_32x32x16_bf16 v[80:95], v[208:211], v[246:249], v[80:95]
	ds_read_b128 v[230:233], v250 offset:4096
	v_mfma_f32_32x32x16_bf16 v[16:31], v[212:215], v[246:249], v[16:31]
	ds_read_b128 v[234:237], v250 offset:6144
	s_waitcnt lgkmcnt(6)
	v_mfma_f32_32x32x16_bf16 v[64:79], v[208:211], v[192:195], v[64:79]
	v_mfma_f32_32x32x16_bf16 v[0:15], v[212:215], v[192:195], v[0:15]
	s_barrier
	v_xad_u32 v191, v187, 64, s41
	v_xad_u32 v251, v189, 64, s41
	s_waitcnt lgkmcnt(3)
	v_mfma_f32_32x32x16_bf16 v[112:127], v[200:203], v[222:225], v[112:127]
	ds_read_b128 v[208:211], v191
	v_mfma_f32_32x32x16_bf16 v[48:63], v[204:207], v[222:225], v[48:63]
	ds_read_b128 v[212:215], v191 offset:2048
	s_waitcnt lgkmcnt(4)
	v_mfma_f32_32x32x16_bf16 v[96:111], v[200:203], v[226:229], v[96:111]
	ds_read_b128 v[238:241], v251
	s_waitcnt vmcnt(11)
	ds_write_b128 v185, v[128:131]
	v_mfma_f32_32x32x16_bf16 v[32:47], v[204:207], v[226:229], v[32:47]
	ds_read_b128 v[242:245], v251 offset:2048
	s_waitcnt vmcnt(10)
	ds_write_b128 v185, v[132:135] offset:2048
	s_waitcnt lgkmcnt(7)
	v_mfma_f32_32x32x16_bf16 v[80:95], v[200:203], v[230:233], v[80:95]
	ds_read_b128 v[246:249], v251 offset:4096
	s_waitcnt vmcnt(9)
	ds_write_b128 v185, v[136:139] offset:4096
	v_mfma_f32_32x32x16_bf16 v[16:31], v[204:207], v[230:233], v[16:31]
	ds_read_b128 v[192:195], v251 offset:6144
	s_waitcnt vmcnt(8)
	ds_write_b128 v185, v[140:143] offset:6144
	s_waitcnt lgkmcnt(10)
	v_mfma_f32_32x32x16_bf16 v[64:79], v[200:203], v[234:237], v[64:79]
	s_waitcnt vmcnt(7)
	ds_write_b128 v185, v[144:147] offset:8192
	v_mfma_f32_32x32x16_bf16 v[0:15], v[204:207], v[234:237], v[0:15]
	s_waitcnt vmcnt(6)
	ds_write_b128 v185, v[148:151] offset:10240
	s_waitcnt lgkmcnt(9)
	v_mfma_f32_32x32x16_bf16 v[112:127], v[208:211], v[238:241], v[112:127]
	s_waitcnt vmcnt(5)
	ds_write_b128 v185, v[152:155] offset:12288
	v_mfma_f32_32x32x16_bf16 v[48:63], v[212:215], v[238:241], v[48:63]
	s_waitcnt vmcnt(4)
	ds_write_b128 v185, v[156:159] offset:14336
	s_waitcnt lgkmcnt(9)
	v_mfma_f32_32x32x16_bf16 v[96:111], v[208:211], v[242:245], v[96:111]
	s_waitcnt vmcnt(3)
	ds_write_b128 v185, v[160:163] offset:16384
	v_mfma_f32_32x32x16_bf16 v[32:47], v[212:215], v[242:245], v[32:47]
	s_waitcnt vmcnt(2)
	ds_write_b128 v185, v[164:167] offset:18432
	s_waitcnt lgkmcnt(9)
	v_mfma_f32_32x32x16_bf16 v[80:95], v[208:211], v[246:249], v[80:95]
	s_waitcnt vmcnt(1)
	ds_write_b128 v185, v[168:171] offset:20480
	v_mfma_f32_32x32x16_bf16 v[16:31], v[212:215], v[246:249], v[16:31]
	s_waitcnt vmcnt(0)
	ds_write_b128 v185, v[172:175] offset:22528
	s_waitcnt lgkmcnt(9)
	v_mfma_f32_32x32x16_bf16 v[64:79], v[208:211], v[192:195], v[64:79]
	v_mfma_f32_32x32x16_bf16 v[0:15], v[212:215], v[192:195], v[0:15]
	s_add_u32 s28, s28, 0x80
	s_addc_u32 s29, s29, 0
	s_add_u32 s38, s38, 0x80
	s_addc_u32 s39, s39, 0
	s_sub_i32 s40, s40, 0x6000
	s_cmp_lt_i32 s40, 0
	s_cselect_b32 s42, 0x12000, 0
	s_add_i32 s40, s40, s42
	s_sub_i32 s41, s41, 0x6000
	s_cmp_lt_i32 s41, 0
	s_cselect_b32 s42, 0x12000, 0
	s_add_i32 s41, s41, s42
	v_subrev_u32_e32 v196, 0x6000, v185
	v_add_u32_e32 v198, 0xc000, v185
	v_min_u32_e32 v185, v196, v198
	s_add_i32 s7, s7, 1
	s_cmp_lt_u32 s7, 15
	s_waitcnt lgkmcnt(0)
	s_barrier
	s_cbranch_scc1 .Lg4_loop
	v_add_u32_e32 v190, s40, v186
	v_add_u32_e32 v191, s40, v187
	v_add_u32_e32 v250, s40, v188
	v_add_u32_e32 v251, s40, v189
	ds_read_b128 v[200:203], v190
	ds_read_b128 v[204:207], v190 offset:2048
	ds_read_b128 v[222:225], v250
	ds_read_b128 v[226:229], v250 offset:2048
	ds_read_b128 v[230:233], v250 offset:4096
	ds_read_b128 v[234:237], v250 offset:6144
	s_waitcnt lgkmcnt(3)
	v_mfma_f32_32x32x16_bf16 v[112:127], v[200:203], v[222:225], v[112:127]
	ds_read_b128 v[208:211], v191
	v_mfma_f32_32x32x16_bf16 v[48:63], v[204:207], v[222:225], v[48:63]
	ds_read_b128 v[212:215], v191 offset:2048
	s_waitcnt lgkmcnt(4)
	v_mfma_f32_32x32x16_bf16 v[96:111], v[200:203], v[226:229], v[96:111]
	ds_read_b128 v[238:241], v251
	v_mfma_f32_32x32x16_bf16 v[32:47], v[204:207], v[226:229], v[32:47]
	ds_read_b128 v[242:245], v251 offset:2048
	s_waitcnt lgkmcnt(5)
	v_mfma_f32_32x32x16_bf16 v[80:95], v[200:203], v[230:233], v[80:95]
	ds_read_b128 v[246:249], v251 offset:4096
	v_mfma_f32_32x32x16_bf16 v[16:31], v[204:207], v[230:233], v[16:31]
	ds_read_b128 v[192:195], v251 offset:6144
	s_waitcnt lgkmcnt(6)
	v_mfma_f32_32x32x16_bf16 v[64:79], v[200:203], v[234:237], v[64:79]
	v_mfma_f32_32x32x16_bf16 v[0:15], v[204:207], v[234:237], v[0:15]
	v_xad_u32 v190, v186, 64, s41
	v_xad_u32 v250, v188, 64, s41
	s_waitcnt lgkmcnt(3)
	v_mfma_f32_32x32x16_bf16 v[112:127], v[208:211], v[238:241], v[112:127]
	ds_read_b128 v[200:203], v190
	v_mfma_f32_32x32x16_bf16 v[48:63], v[212:215], v[238:241], v[48:63]
	ds_read_b128 v[204:207], v190 offset:2048
	s_waitcnt lgkmcnt(4)
	v_mfma_f32_32x32x16_bf16 v[96:111], v[208:211], v[242:245], v[96:111]
	ds_read_b128 v[222:225], v250
	v_mfma_f32_32x32x16_bf16 v[32:47], v[212:215], v[242:245], v[32:47]
	ds_read_b128 v[226:229], v250 offset:2048
	s_waitcnt lgkmcnt(5)
	v_mfma_f32_32x32x16_bf16 v[80:95], v[208:211], v[246:249], v[80:95]
	ds_read_b128 v[230:233], v250 offset:4096
	v_mfma_f32_32x32x16_bf16 v[16:31], v[212:215], v[246:249], v[16:31]
	ds_read_b128 v[234:237], v250 offset:6144
	s_waitcnt lgkmcnt(6)
	v_mfma_f32_32x32x16_bf16 v[64:79], v[208:211], v[192:195], v[64:79]
	v_mfma_f32_32x32x16_bf16 v[0:15], v[212:215], v[192:195], v[0:15]
	v_xad_u32 v191, v187, 64, s41
	v_xad_u32 v251, v189, 64, s41
	s_waitcnt lgkmcnt(3)
	v_mfma_f32_32x32x16_bf16 v[112:127], v[200:203], v[222:225], v[112:127]
	ds_read_b128 v[208:211], v191
	v_mfma_f32_32x32x16_bf16 v[48:63], v[204:207], v[222:225], v[48:63]
	ds_read_b128 v[212:215], v191 offset:2048
	s_waitcnt lgkmcnt(4)
	v_mfma_f32_32x32x16_bf16 v[96:111], v[200:203], v[226:229], v[96:111]
	ds_read_b128 v[238:241], v251
	v_mfma_f32_32x32x16_bf16 v[32:47], v[204:207], v[226:229], v[32:47]
	ds_read_b128 v[242:245], v251 offset:2048
	s_waitcnt lgkmcnt(5)
	v_mfma_f32_32x32x16_bf16 v[80:95], v[200:203], v[230:233], v[80:95]
	ds_read_b128 v[246:249], v251 offset:4096
	v_mfma_f32_32x32x16_bf16 v[16:31], v[204:207], v[230:233], v[16:31]
	ds_read_b128 v[192:195], v251 offset:6144
	s_waitcnt lgkmcnt(6)
	v_mfma_f32_32x32x16_bf16 v[64:79], v[200:203], v[234:237], v[64:79]
	v_mfma_f32_32x32x16_bf16 v[0:15], v[204:207], v[234:237], v[0:15]
	s_waitcnt lgkmcnt(3)
	v_mfma_f32_32x32x16_bf16 v[112:127], v[208:211], v[238:241], v[112:127]
	v_mfma_f32_32x32x16_bf16 v[48:63], v[212:215], v[238:241], v[48:63]
	s_waitcnt lgkmcnt(2)
	v_mfma_f32_32x32x16_bf16 v[96:111], v[208:211], v[242:245], v[96:111]
	v_mfma_f32_32x32x16_bf16 v[32:47], v[212:215], v[242:245], v[32:47]
	s_waitcnt lgkmcnt(1)
	v_mfma_f32_32x32x16_bf16 v[80:95], v[208:211], v[246:249], v[80:95]
	v_mfma_f32_32x32x16_bf16 v[16:31], v[212:215], v[246:249], v[16:31]
	s_waitcnt lgkmcnt(0)
	v_mfma_f32_32x32x16_bf16 v[64:79], v[208:211], v[192:195], v[64:79]
	v_mfma_f32_32x32x16_bf16 v[0:15], v[212:215], v[192:195], v[0:15]
	s_setprio 0
	s_nop 7
	s_nop 7

.LBB0_488:
	s_or_b64 exec, exec, s[26:27]
	s_lshl_b32 s6, s7, 8
	s_lshl_b64 s[40:41], s[0:1], 11
	s_add_u32 s42, s66, s40
	s_addc_u32 s43, s67, s41
	s_lshl_b32 s7, s7, 19
	s_add_u32 s44, s2, s7
	s_addc_u32 s45, s3, 0
	v_lshrrev_b32_e32 v196, 3, v197
	v_and_b32_e32 v198, 7, v197
	v_lshlrev_b32_e32 v178, 11, v196
	v_lshl_or_b32 v178, v198, 4, v178
	v_add_u32_e32 v179, 0x10000, v178
	v_add_u32_e32 v180, 0x20000, v178
	v_add_u32_e32 v181, 0x30000, v178
	v_add_u32_e32 v182, 0x40000, v178
	v_add_u32_e32 v183, 0x50000, v178
	v_add_u32_e32 v184, 0x60000, v178
	v_add_u32_e32 v185, 0x70000, v178
	global_load_dwordx4 v[128:131], v178, s[42:43]
	global_load_dwordx4 v[132:135], v179, s[42:43]
	global_load_dwordx4 v[136:139], v180, s[42:43]
	global_load_dwordx4 v[140:143], v181, s[42:43]
	global_load_dwordx4 v[144:147], v178, s[44:45]
	global_load_dwordx4 v[148:151], v179, s[44:45]
	global_load_dwordx4 v[152:155], v180, s[44:45]
	global_load_dwordx4 v[156:159], v181, s[44:45]
	global_load_dwordx4 v[160:163], v182, s[44:45]
	global_load_dwordx4 v[164:167], v183, s[44:45]
	global_load_dwordx4 v[168:171], v184, s[44:45]
	global_load_dwordx4 v[172:175], v185, s[44:45]
	s_add_u32 s42, s42, 0x80
	s_addc_u32 s43, s43, 0
	s_add_u32 s44, s44, 0x80
	s_addc_u32 s45, s45, 0
	v_bfe_u32 v217, v197, 5, 2
	v_and_b32_e32 v218, 3, v198
	v_xor_b32_e32 v218, v218, v217
	v_lshlrev_b32_e32 v218, 4, v218
	v_lshl_or_b32 v177, v196, 6, v218
	v_lshrrev_b32_e32 v217, 2, v198
	v_lshlrev_b32_e32 v218, 6, v217
	v_xor_b32_e32 v177, v177, v218
	v_mul_u32_u24_e32 v217, 0x6000, v217
	v_add_u32_e32 v177, v177, v217
	v_and_b32_e32 v196, 31, v197
	v_bfe_u32 v198, v197, 5, 1
	v_bfe_u32 v217, v197, 2, 2
	v_xor_b32_e32 v218, v198, v217
	v_xor_b32_e32 v221, 2, v218
	v_lshrrev_b32_e32 v198, 7, v197
	v_lshl_or_b32 v198, v198, 6, v196
	v_lshlrev_b32_e32 v198, 6, v198
	v_lshl_or_b32 v186, v218, 4, v198
	v_lshl_or_b32 v187, v221, 4, v198
	v_bfe_u32 v198, v197, 6, 1
	v_mul_u32_u24_e32 v198, 128, v198
	v_add_u32_e32 v198, v198, v196
	v_lshlrev_b32_e32 v198, 6, v198
	v_add_u32_e32 v198, 0x2000, v198
	v_lshl_or_b32 v188, v218, 4, v198
	v_lshl_or_b32 v189, v221, 4, v198
	v_mov_b64_e32 v[0:1], 0
	v_mov_b64_e32 v[2:3], 0
	v_mov_b64_e32 v[4:5], 0
	v_mov_b64_e32 v[6:7], 0
	v_mov_b64_e32 v[8:9], 0
	v_mov_b64_e32 v[10:11], 0
	v_mov_b64_e32 v[12:13], 0
	v_mov_b64_e32 v[14:15], 0
	v_mov_b64_e32 v[16:17], 0
	v_mov_b64_e32 v[18:19], 0
	v_mov_b64_e32 v[20:21], 0
	v_mov_b64_e32 v[22:23], 0
	v_mov_b64_e32 v[24:25], 0
	v_mov_b64_e32 v[26:27], 0
	v_mov_b64_e32 v[28:29], 0
	v_mov_b64_e32 v[30:31], 0
	v_mov_b64_e32 v[32:33], 0
	v_mov_b64_e32 v[34:35], 0
	v_mov_b64_e32 v[36:37], 0
	v_mov_b64_e32 v[38:39], 0
	v_mov_b64_e32 v[40:41], 0
	v_mov_b64_e32 v[42:43], 0
	v_mov_b64_e32 v[44:45], 0
	v_mov_b64_e32 v[46:47], 0
	v_mov_b64_e32 v[48:49], 0
	v_mov_b64_e32 v[50:51], 0
	v_mov_b64_e32 v[52:53], 0
	v_mov_b64_e32 v[54:55], 0
	v_mov_b64_e32 v[56:57], 0
	v_mov_b64_e32 v[58:59], 0
	v_mov_b64_e32 v[60:61], 0
	v_mov_b64_e32 v[62:63], 0
	v_mov_b64_e32 v[64:65], 0
	v_mov_b64_e32 v[66:67], 0
	v_mov_b64_e32 v[68:69], 0
	v_mov_b64_e32 v[70:71], 0
	v_mov_b64_e32 v[72:73], 0
	v_mov_b64_e32 v[74:75], 0
	v_mov_b64_e32 v[76:77], 0
	v_mov_b64_e32 v[78:79], 0
	v_mov_b64_e32 v[80:81], 0
	v_mov_b64_e32 v[82:83], 0
	v_mov_b64_e32 v[84:85], 0
	v_mov_b64_e32 v[86:87], 0
	v_mov_b64_e32 v[88:89], 0
	v_mov_b64_e32 v[90:91], 0
	v_mov_b64_e32 v[92:93], 0
	v_mov_b64_e32 v[94:95], 0
	v_mov_b64_e32 v[96:97], 0
	v_mov_b64_e32 v[98:99], 0
	v_mov_b64_e32 v[100:101], 0
	v_mov_b64_e32 v[102:103], 0
	v_mov_b64_e32 v[104:105], 0
	v_mov_b64_e32 v[106:107], 0
	v_mov_b64_e32 v[108:109], 0
	v_mov_b64_e32 v[110:111], 0
	v_mov_b64_e32 v[112:113], 0
	v_mov_b64_e32 v[114:115], 0
	v_mov_b64_e32 v[116:117], 0
	v_mov_b64_e32 v[118:119], 0
	v_mov_b64_e32 v[120:121], 0
	v_mov_b64_e32 v[122:123], 0
	v_mov_b64_e32 v[124:125], 0
	v_mov_b64_e32 v[126:127], 0
	s_mov_b32 s36, 0
	s_mov_b32 s37, 0x6000
	s_mov_b32 s1, 0
	s_waitcnt vmcnt(11)
	ds_write_b128 v177, v[128:131]
	s_waitcnt vmcnt(10)
	ds_write_b128 v177, v[132:135] offset:2048
	s_waitcnt vmcnt(9)
	ds_write_b128 v177, v[136:139] offset:4096
	s_waitcnt vmcnt(8)
	ds_write_b128 v177, v[140:143] offset:6144
	s_waitcnt vmcnt(7)
	ds_write_b128 v177, v[144:147] offset:8192
	s_waitcnt vmcnt(6)
	ds_write_b128 v177, v[148:151] offset:10240
	s_waitcnt vmcnt(5)
	ds_write_b128 v177, v[152:155] offset:12288
	s_waitcnt vmcnt(4)
	ds_write_b128 v177, v[156:159] offset:14336
	s_waitcnt vmcnt(3)
	ds_write_b128 v177, v[160:163] offset:16384
	s_waitcnt vmcnt(2)
	ds_write_b128 v177, v[164:167] offset:18432
	s_waitcnt vmcnt(1)
	ds_write_b128 v177, v[168:171] offset:20480
	s_waitcnt vmcnt(0)
	ds_write_b128 v177, v[172:175] offset:22528
	v_subrev_u32_e32 v196, 0x6000, v177
	v_add_u32_e32 v198, 0xc000, v177
	v_min_u32_e32 v177, v196, v198
	s_waitcnt lgkmcnt(0)
	s_barrier
	s_getreg_b32 s38, hwreg(HW_REG_HW_ID, 0, 4)
	s_bitcmp1_b32 s38, 0
	s_cbranch_scc0 .Lg5_noraise
	s_setprio 1
.Lg5_noraise:
.Lg5_loop:
	v_add_u32_e32 v190, s36, v186
	v_add_u32_e32 v191, s36, v187
	v_add_u32_e32 v250, s36, v188
	v_add_u32_e32 v251, s36, v189
	ds_read_b128 v[200:203], v190
	ds_read_b128 v[204:207], v190 offset:2048
	ds_read_b128 v[222:225], v250
	ds_read_b128 v[226:229], v250 offset:2048
	ds_read_b128 v[230:233], v250 offset:4096
	ds_read_b128 v[234:237], v250 offset:6144
	s_waitcnt lgkmcnt(3)
	v_mfma_f32_32x32x16_bf16 v[112:127], v[200:203], v[222:225], v[112:127]
	global_load_dwordx4 v[128:131], v178, s[42:43]
	ds_read_b128 v[208:211], v191
	v_mfma_f32_32x32x16_bf16 v[48:63], v[204:207], v[222:225], v[48:63]
	global_load_dwordx4 v[132:135], v179, s[42:43]
	ds_read_b128 v[212:215], v191 offset:2048
	s_waitcnt lgkmcnt(4)
	v_mfma_f32_32x32x16_bf16 v[96:111], v[200:203], v[226:229], v[96:111]
	global_load_dwordx4 v[136:139], v180, s[42:43]
	ds_read_b128 v[238:241], v251
	v_mfma_f32_32x32x16_bf16 v[32:47], v[204:207], v[226:229], v[32:47]
	global_load_dwordx4 v[140:143], v181, s[42:43]
	ds_read_b128 v[242:245], v251 offset:2048
	s_waitcnt lgkmcnt(5)
	v_mfma_f32_32x32x16_bf16 v[80:95], v[200:203], v[230:233], v[80:95]
	global_load_dwordx4 v[144:147], v178, s[44:45]
	ds_read_b128 v[246:249], v251 offset:4096
	v_mfma_f32_32x32x16_bf16 v[16:31], v[204:207], v[230:233], v[16:31]
	global_load_dwordx4 v[148:151], v179, s[44:45]
	ds_read_b128 v[192:195], v251 offset:6144
	s_waitcnt lgkmcnt(6)
	v_mfma_f32_32x32x16_bf16 v[64:79], v[200:203], v[234:237], v[64:79]
	global_load_dwordx4 v[152:155], v180, s[44:45]
	v_mfma_f32_32x32x16_bf16 v[0:15], v[204:207], v[234:237], v[0:15]
	global_load_dwordx4 v[156:159], v181, s[44:45]
	v_xad_u32 v190, v186, 64, s37
	v_xad_u32 v250, v188, 64, s37
	s_waitcnt lgkmcnt(3)
	v_mfma_f32_32x32x16_bf16 v[112:127], v[208:211], v[238:241], v[112:127]
	global_load_dwordx4 v[160:163], v182, s[44:45]
	ds_read_b128 v[200:203], v190
	v_mfma_f32_32x32x16_bf16 v[48:63], v[212:215], v[238:241], v[48:63]
	global_load_dwordx4 v[164:167], v183, s[44:45]
	ds_read_b128 v[204:207], v190 offset:2048
	s_waitcnt lgkmcnt(4)
	v_mfma_f32_32x32x16_bf16 v[96:111], v[208:211], v[242:245], v[96:111]
	global_load_dwordx4 v[168:171], v184, s[44:45]
	ds_read_b128 v[222:225], v250
	v_mfma_f32_32x32x16_bf16 v[32:47], v[212:215], v[242:245], v[32:47]
	global_load_dwordx4 v[172:175], v185, s[44:45]
	ds_read_b128 v[226:229], v250 offset:2048
	s_waitcnt lgkmcnt(5)
	v_mfma_f32_32x32x16_bf16 v[80:95], v[208:211], v[246:249], v[80:95]
	ds_read_b128 v[230:233], v250 offset:4096
	v_mfma_f32_32x32x16_bf16 v[16:31], v[212:215], v[246:249], v[16:31]
	ds_read_b128 v[234:237], v250 offset:6144
	s_waitcnt lgkmcnt(6)
	v_mfma_f32_32x32x16_bf16 v[64:79], v[208:211], v[192:195], v[64:79]
	v_mfma_f32_32x32x16_bf16 v[0:15], v[212:215], v[192:195], v[0:15]
	s_barrier
	v_xad_u32 v191, v187, 64, s37
	v_xad_u32 v251, v189, 64, s37
	s_waitcnt lgkmcnt(3)
	v_mfma_f32_32x32x16_bf16 v[112:127], v[200:203], v[222:225], v[112:127]
	ds_read_b128 v[208:211], v191
	v_mfma_f32_32x32x16_bf16 v[48:63], v[204:207], v[222:225], v[48:63]
	ds_read_b128 v[212:215], v191 offset:2048
	s_waitcnt lgkmcnt(4)
	v_mfma_f32_32x32x16_bf16 v[96:111], v[200:203], v[226:229], v[96:111]
	ds_read_b128 v[238:241], v251
	s_waitcnt vmcnt(11)
	ds_write_b128 v177, v[128:131]
	v_mfma_f32_32x32x16_bf16 v[32:47], v[204:207], v[226:229], v[32:47]
	ds_read_b128 v[242:245], v251 offset:2048
	s_waitcnt vmcnt(10)
	ds_write_b128 v177, v[132:135] offset:2048
	s_waitcnt lgkmcnt(7)
	v_mfma_f32_32x32x16_bf16 v[80:95], v[200:203], v[230:233], v[80:95]
	ds_read_b128 v[246:249], v251 offset:4096
	s_waitcnt vmcnt(9)
	ds_write_b128 v177, v[136:139] offset:4096
	v_mfma_f32_32x32x16_bf16 v[16:31], v[204:207], v[230:233], v[16:31]
	ds_read_b128 v[192:195], v251 offset:6144
	s_waitcnt vmcnt(8)
	ds_write_b128 v177, v[140:143] offset:6144
	s_waitcnt lgkmcnt(10)
	v_mfma_f32_32x32x16_bf16 v[64:79], v[200:203], v[234:237], v[64:79]
	s_waitcnt vmcnt(7)
	ds_write_b128 v177, v[144:147] offset:8192
	v_mfma_f32_32x32x16_bf16 v[0:15], v[204:207], v[234:237], v[0:15]
	s_waitcnt vmcnt(6)
	ds_write_b128 v177, v[148:151] offset:10240
	s_waitcnt lgkmcnt(9)
	v_mfma_f32_32x32x16_bf16 v[112:127], v[208:211], v[238:241], v[112:127]
	s_waitcnt vmcnt(5)
	ds_write_b128 v177, v[152:155] offset:12288
	v_mfma_f32_32x32x16_bf16 v[48:63], v[212:215], v[238:241], v[48:63]
	s_waitcnt vmcnt(4)
	ds_write_b128 v177, v[156:159] offset:14336
	s_waitcnt lgkmcnt(9)
	v_mfma_f32_32x32x16_bf16 v[96:111], v[208:211], v[242:245], v[96:111]
	s_waitcnt vmcnt(3)
	ds_write_b128 v177, v[160:163] offset:16384
	v_mfma_f32_32x32x16_bf16 v[32:47], v[212:215], v[242:245], v[32:47]
	s_waitcnt vmcnt(2)
	ds_write_b128 v177, v[164:167] offset:18432
	s_waitcnt lgkmcnt(9)
	v_mfma_f32_32x32x16_bf16 v[80:95], v[208:211], v[246:249], v[80:95]
	s_waitcnt vmcnt(1)
	ds_write_b128 v177, v[168:171] offset:20480
	v_mfma_f32_32x32x16_bf16 v[16:31], v[212:215], v[246:249], v[16:31]
	s_waitcnt vmcnt(0)
	ds_write_b128 v177, v[172:175] offset:22528
	s_waitcnt lgkmcnt(9)
	v_mfma_f32_32x32x16_bf16 v[64:79], v[208:211], v[192:195], v[64:79]
	v_mfma_f32_32x32x16_bf16 v[0:15], v[212:215], v[192:195], v[0:15]
	s_add_u32 s42, s42, 0x80
	s_addc_u32 s43, s43, 0
	s_add_u32 s44, s44, 0x80
	s_addc_u32 s45, s45, 0
	s_sub_i32 s36, s36, 0x6000
	s_cmp_lt_i32 s36, 0
	s_cselect_b32 s38, 0x12000, 0
	s_add_i32 s36, s36, s38
	s_sub_i32 s37, s37, 0x6000
	s_cmp_lt_i32 s37, 0
	s_cselect_b32 s38, 0x12000, 0
	s_add_i32 s37, s37, s38
	v_subrev_u32_e32 v196, 0x6000, v177
	v_add_u32_e32 v198, 0xc000, v177
	v_min_u32_e32 v177, v196, v198
	s_add_i32 s1, s1, 1
	s_cmp_lt_u32 s1, 15
	s_waitcnt lgkmcnt(0)
	s_barrier
	s_cbranch_scc1 .Lg5_loop
	v_add_u32_e32 v190, s36, v186
	v_add_u32_e32 v191, s36, v187
	v_add_u32_e32 v250, s36, v188
	v_add_u32_e32 v251, s36, v189
	ds_read_b128 v[200:203], v190
	ds_read_b128 v[204:207], v190 offset:2048
	ds_read_b128 v[222:225], v250
	ds_read_b128 v[226:229], v250 offset:2048
	ds_read_b128 v[230:233], v250 offset:4096
	ds_read_b128 v[234:237], v250 offset:6144
	s_waitcnt lgkmcnt(3)
	v_mfma_f32_32x32x16_bf16 v[112:127], v[200:203], v[222:225], v[112:127]
	ds_read_b128 v[208:211], v191
	v_mfma_f32_32x32x16_bf16 v[48:63], v[204:207], v[222:225], v[48:63]
	ds_read_b128 v[212:215], v191 offset:2048
	s_waitcnt lgkmcnt(4)
	v_mfma_f32_32x32x16_bf16 v[96:111], v[200:203], v[226:229], v[96:111]
	ds_read_b128 v[238:241], v251
	v_mfma_f32_32x32x16_bf16 v[32:47], v[204:207], v[226:229], v[32:47]
	ds_read_b128 v[242:245], v251 offset:2048
	s_waitcnt lgkmcnt(5)
	v_mfma_f32_32x32x16_bf16 v[80:95], v[200:203], v[230:233], v[80:95]
	ds_read_b128 v[246:249], v251 offset:4096
	v_mfma_f32_32x32x16_bf16 v[16:31], v[204:207], v[230:233], v[16:31]
	ds_read_b128 v[192:195], v251 offset:6144
	s_waitcnt lgkmcnt(6)
	v_mfma_f32_32x32x16_bf16 v[64:79], v[200:203], v[234:237], v[64:79]
	v_mfma_f32_32x32x16_bf16 v[0:15], v[204:207], v[234:237], v[0:15]
	v_xad_u32 v190, v186, 64, s37
	v_xad_u32 v250, v188, 64, s37
	s_waitcnt lgkmcnt(3)
	v_mfma_f32_32x32x16_bf16 v[112:127], v[208:211], v[238:241], v[112:127]
	ds_read_b128 v[200:203], v190
	v_mfma_f32_32x32x16_bf16 v[48:63], v[212:215], v[238:241], v[48:63]
	ds_read_b128 v[204:207], v190 offset:2048
	s_waitcnt lgkmcnt(4)
	v_mfma_f32_32x32x16_bf16 v[96:111], v[208:211], v[242:245], v[96:111]
	ds_read_b128 v[222:225], v250
	v_mfma_f32_32x32x16_bf16 v[32:47], v[212:215], v[242:245], v[32:47]
	ds_read_b128 v[226:229], v250 offset:2048
	s_waitcnt lgkmcnt(5)
	v_mfma_f32_32x32x16_bf16 v[80:95], v[208:211], v[246:249], v[80:95]
	ds_read_b128 v[230:233], v250 offset:4096
	v_mfma_f32_32x32x16_bf16 v[16:31], v[212:215], v[246:249], v[16:31]
	ds_read_b128 v[234:237], v250 offset:6144
	s_waitcnt lgkmcnt(6)
	v_mfma_f32_32x32x16_bf16 v[64:79], v[208:211], v[192:195], v[64:79]
	v_mfma_f32_32x32x16_bf16 v[0:15], v[212:215], v[192:195], v[0:15]
	v_xad_u32 v191, v187, 64, s37
	v_xad_u32 v251, v189, 64, s37
	s_waitcnt lgkmcnt(3)
	v_mfma_f32_32x32x16_bf16 v[112:127], v[200:203], v[222:225], v[112:127]
	ds_read_b128 v[208:211], v191
	v_mfma_f32_32x32x16_bf16 v[48:63], v[204:207], v[222:225], v[48:63]
	ds_read_b128 v[212:215], v191 offset:2048
	s_waitcnt lgkmcnt(4)
	v_mfma_f32_32x32x16_bf16 v[96:111], v[200:203], v[226:229], v[96:111]
	ds_read_b128 v[238:241], v251
	v_mfma_f32_32x32x16_bf16 v[32:47], v[204:207], v[226:229], v[32:47]
	ds_read_b128 v[242:245], v251 offset:2048
	s_waitcnt lgkmcnt(5)
	v_mfma_f32_32x32x16_bf16 v[80:95], v[200:203], v[230:233], v[80:95]
	ds_read_b128 v[246:249], v251 offset:4096
	v_mfma_f32_32x32x16_bf16 v[16:31], v[204:207], v[230:233], v[16:31]
	ds_read_b128 v[192:195], v251 offset:6144
	s_waitcnt lgkmcnt(6)
	v_mfma_f32_32x32x16_bf16 v[64:79], v[200:203], v[234:237], v[64:79]
	v_mfma_f32_32x32x16_bf16 v[0:15], v[204:207], v[234:237], v[0:15]
	s_waitcnt lgkmcnt(3)
	v_mfma_f32_32x32x16_bf16 v[112:127], v[208:211], v[238:241], v[112:127]
	v_mfma_f32_32x32x16_bf16 v[48:63], v[212:215], v[238:241], v[48:63]
	s_waitcnt lgkmcnt(2)
	v_mfma_f32_32x32x16_bf16 v[96:111], v[208:211], v[242:245], v[96:111]
	v_mfma_f32_32x32x16_bf16 v[32:47], v[212:215], v[242:245], v[32:47]
	s_waitcnt lgkmcnt(1)
	v_mfma_f32_32x32x16_bf16 v[80:95], v[208:211], v[246:249], v[80:95]
	v_mfma_f32_32x32x16_bf16 v[16:31], v[212:215], v[246:249], v[16:31]
	s_waitcnt lgkmcnt(0)
	v_mfma_f32_32x32x16_bf16 v[64:79], v[208:211], v[192:195], v[64:79]
	v_mfma_f32_32x32x16_bf16 v[0:15], v[212:215], v[192:195], v[0:15]
	s_setprio 0
	s_nop 7
	s_nop 7
	s_branch .LBB0_482

.LBB0_551:
	s_lshl_b32 s6, s5, 5
	s_and_b32 s26, s6, 0xffffff80
	s_lshl_b32 s6, s5, 8
	s_ashr_i32 s27, s26, 31
	s_and_b32 s68, s6, 0x300
	s_lshl_b64 s[8:9], s[26:27], 13
	s_add_u32 s28, s70, s8
	s_addc_u32 s29, s71, s9
	s_lshl_b32 s7, s68, 13
	s_add_u32 s38, s80, s7
	s_addc_u32 s39, s81, 0
	v_lshrrev_b32_e32 v196, 3, v197
	v_and_b32_e32 v198, 7, v197
	v_lshlrev_b32_e32 v176, 13, v196
	v_lshl_or_b32 v176, v198, 4, v176
	v_add_u32_e32 v177, 0x40000, v176
	v_add_u32_e32 v178, 0x80000, v176
	v_add_u32_e32 v179, 0xc0000, v176
	v_add_u32_e32 v180, 0x100000, v176
	v_add_u32_e32 v181, 0x140000, v176
	v_add_u32_e32 v182, 0x180000, v176
	v_add_u32_e32 v184, 0x1c0000, v176
	global_load_dwordx4 v[128:131], v176, s[28:29]
	global_load_dwordx4 v[132:135], v177, s[28:29]
	global_load_dwordx4 v[136:139], v178, s[28:29]
	global_load_dwordx4 v[140:143], v179, s[28:29]
	global_load_dwordx4 v[144:147], v176, s[38:39]
	global_load_dwordx4 v[148:151], v177, s[38:39]
	global_load_dwordx4 v[152:155], v178, s[38:39]
	global_load_dwordx4 v[156:159], v179, s[38:39]
	global_load_dwordx4 v[160:163], v180, s[38:39]
	global_load_dwordx4 v[164:167], v181, s[38:39]
	global_load_dwordx4 v[168:171], v182, s[38:39]
	global_load_dwordx4 v[172:175], v184, s[38:39]
	s_add_u32 s28, s28, 0x80
	s_addc_u32 s29, s29, 0
	s_add_u32 s38, s38, 0x80
	s_addc_u32 s39, s39, 0
	v_bfe_u32 v217, v197, 5, 2
	v_and_b32_e32 v218, 3, v198
	v_xor_b32_e32 v218, v218, v217
	v_lshlrev_b32_e32 v218, 4, v218
	v_lshl_or_b32 v185, v196, 6, v218
	v_lshrrev_b32_e32 v217, 2, v198
	v_lshlrev_b32_e32 v218, 6, v217
	v_xor_b32_e32 v185, v185, v218
	v_mul_u32_u24_e32 v217, 0x6000, v217
	v_add_u32_e32 v185, v185, v217
	v_and_b32_e32 v196, 31, v197
	v_bfe_u32 v198, v197, 5, 1
	v_bfe_u32 v217, v197, 2, 2
	v_xor_b32_e32 v218, v198, v217
	v_xor_b32_e32 v221, 2, v218
	v_lshrrev_b32_e32 v198, 7, v197
	v_lshl_or_b32 v198, v198, 6, v196
	v_lshlrev_b32_e32 v198, 6, v198
	v_lshl_or_b32 v186, v218, 4, v198
	v_lshl_or_b32 v187, v221, 4, v198
	v_bfe_u32 v198, v197, 6, 1
	v_mul_u32_u24_e32 v198, 128, v198
	v_add_u32_e32 v198, v198, v196
	v_lshlrev_b32_e32 v198, 6, v198
	v_add_u32_e32 v198, 0x2000, v198
	v_lshl_or_b32 v188, v218, 4, v198
	v_lshl_or_b32 v189, v221, 4, v198
	v_mov_b64_e32 v[0:1], 0
	v_mov_b64_e32 v[2:3], 0
	v_mov_b64_e32 v[4:5], 0
	v_mov_b64_e32 v[6:7], 0
	v_mov_b64_e32 v[8:9], 0
	v_mov_b64_e32 v[10:11], 0
	v_mov_b64_e32 v[12:13], 0
	v_mov_b64_e32 v[14:15], 0
	v_mov_b64_e32 v[16:17], 0
	v_mov_b64_e32 v[18:19], 0
	v_mov_b64_e32 v[20:21], 0
	v_mov_b64_e32 v[22:23], 0
	v_mov_b64_e32 v[24:25], 0
	v_mov_b64_e32 v[26:27], 0
	v_mov_b64_e32 v[28:29], 0
	v_mov_b64_e32 v[30:31], 0
	v_mov_b64_e32 v[32:33], 0
	v_mov_b64_e32 v[34:35], 0
	v_mov_b64_e32 v[36:37], 0
	v_mov_b64_e32 v[38:39], 0
	v_mov_b64_e32 v[40:41], 0
	v_mov_b64_e32 v[42:43], 0
	v_mov_b64_e32 v[44:45], 0
	v_mov_b64_e32 v[46:47], 0
	v_mov_b64_e32 v[48:49], 0
	v_mov_b64_e32 v[50:51], 0
	v_mov_b64_e32 v[52:53], 0
	v_mov_b64_e32 v[54:55], 0
	v_mov_b64_e32 v[56:57], 0
	v_mov_b64_e32 v[58:59], 0
	v_mov_b64_e32 v[60:61], 0
	v_mov_b64_e32 v[62:63], 0
	v_mov_b64_e32 v[64:65], 0
	v_mov_b64_e32 v[66:67], 0
	v_mov_b64_e32 v[68:69], 0
	v_mov_b64_e32 v[70:71], 0
	v_mov_b64_e32 v[72:73], 0
	v_mov_b64_e32 v[74:75], 0
	v_mov_b64_e32 v[76:77], 0
	v_mov_b64_e32 v[78:79], 0
	v_mov_b64_e32 v[80:81], 0
	v_mov_b64_e32 v[82:83], 0
	v_mov_b64_e32 v[84:85], 0
	v_mov_b64_e32 v[86:87], 0
	v_mov_b64_e32 v[88:89], 0
	v_mov_b64_e32 v[90:91], 0
	v_mov_b64_e32 v[92:93], 0
	v_mov_b64_e32 v[94:95], 0
	v_mov_b64_e32 v[96:97], 0
	v_mov_b64_e32 v[98:99], 0
	v_mov_b64_e32 v[100:101], 0
	v_mov_b64_e32 v[102:103], 0
	v_mov_b64_e32 v[104:105], 0
	v_mov_b64_e32 v[106:107], 0
	v_mov_b64_e32 v[108:109], 0
	v_mov_b64_e32 v[110:111], 0
	v_mov_b64_e32 v[112:113], 0
	v_mov_b64_e32 v[114:115], 0
	v_mov_b64_e32 v[116:117], 0
	v_mov_b64_e32 v[118:119], 0
	v_mov_b64_e32 v[120:121], 0
	v_mov_b64_e32 v[122:123], 0
	v_mov_b64_e32 v[124:125], 0
	v_mov_b64_e32 v[126:127], 0
	s_mov_b32 s40, 0
	s_mov_b32 s41, 0x6000
	s_mov_b32 s7, 0
	s_waitcnt vmcnt(11)
	ds_write_b128 v185, v[128:131]
	s_waitcnt vmcnt(10)
	ds_write_b128 v185, v[132:135] offset:2048
	s_waitcnt vmcnt(9)
	ds_write_b128 v185, v[136:139] offset:4096
	s_waitcnt vmcnt(8)
	ds_write_b128 v185, v[140:143] offset:6144
	s_waitcnt vmcnt(7)
	ds_write_b128 v185, v[144:147] offset:8192
	s_waitcnt vmcnt(6)
	ds_write_b128 v185, v[148:151] offset:10240
	s_waitcnt vmcnt(5)
	ds_write_b128 v185, v[152:155] offset:12288
	s_waitcnt vmcnt(4)
	ds_write_b128 v185, v[156:159] offset:14336
	s_waitcnt vmcnt(3)
	ds_write_b128 v185, v[160:163] offset:16384
	s_waitcnt vmcnt(2)
	ds_write_b128 v185, v[164:167] offset:18432
	s_waitcnt vmcnt(1)
	ds_write_b128 v185, v[168:171] offset:20480
	s_waitcnt vmcnt(0)
	ds_write_b128 v185, v[172:175] offset:22528
	v_subrev_u32_e32 v196, 0x6000, v185
	v_add_u32_e32 v198, 0xc000, v185
	v_min_u32_e32 v185, v196, v198
	s_waitcnt lgkmcnt(0)
	s_barrier
	s_getreg_b32 s42, hwreg(HW_REG_HW_ID, 0, 4)
	s_bitcmp1_b32 s42, 0
	s_cbranch_scc0 .Lg6_noraise
	s_setprio 1
.Lg6_noraise:
.Lg6_loop:
	v_add_u32_e32 v190, s40, v186
	v_add_u32_e32 v191, s40, v187
	v_add_u32_e32 v250, s40, v188
	v_add_u32_e32 v251, s40, v189
	ds_read_b128 v[200:203], v190
	ds_read_b128 v[204:207], v190 offset:2048
	ds_read_b128 v[222:225], v250
	ds_read_b128 v[226:229], v250 offset:2048
	ds_read_b128 v[230:233], v250 offset:4096
	ds_read_b128 v[234:237], v250 offset:6144
	s_waitcnt lgkmcnt(3)
	v_mfma_f32_32x32x16_bf16 v[112:127], v[200:203], v[222:225], v[112:127]
	global_load_dwordx4 v[128:131], v176, s[28:29]
	ds_read_b128 v[208:211], v191
	v_mfma_f32_32x32x16_bf16 v[48:63], v[204:207], v[222:225], v[48:63]
	global_load_dwordx4 v[132:135], v177, s[28:29]
	ds_read_b128 v[212:215], v191 offset:2048
	s_waitcnt lgkmcnt(4)
	v_mfma_f32_32x32x16_bf16 v[96:111], v[200:203], v[226:229], v[96:111]
	global_load_dwordx4 v[136:139], v178, s[28:29]
	ds_read_b128 v[238:241], v251
	v_mfma_f32_32x32x16_bf16 v[32:47], v[204:207], v[226:229], v[32:47]
	global_load_dwordx4 v[140:143], v179, s[28:29]
	ds_read_b128 v[242:245], v251 offset:2048
	s_waitcnt lgkmcnt(5)
	v_mfma_f32_32x32x16_bf16 v[80:95], v[200:203], v[230:233], v[80:95]
	global_load_dwordx4 v[144:147], v176, s[38:39]
	ds_read_b128 v[246:249], v251 offset:4096
	v_mfma_f32_32x32x16_bf16 v[16:31], v[204:207], v[230:233], v[16:31]
	global_load_dwordx4 v[148:151], v177, s[38:39]
	ds_read_b128 v[192:195], v251 offset:6144
	s_waitcnt lgkmcnt(6)
	v_mfma_f32_32x32x16_bf16 v[64:79], v[200:203], v[234:237], v[64:79]
	global_load_dwordx4 v[152:155], v178, s[38:39]
	v_mfma_f32_32x32x16_bf16 v[0:15], v[204:207], v[234:237], v[0:15]
	global_load_dwordx4 v[156:159], v179, s[38:39]
	v_xad_u32 v190, v186, 64, s41
	v_xad_u32 v250, v188, 64, s41
	s_waitcnt lgkmcnt(3)
	v_mfma_f32_32x32x16_bf16 v[112:127], v[208:211], v[238:241], v[112:127]
	global_load_dwordx4 v[160:163], v180, s[38:39]
	ds_read_b128 v[200:203], v190
	v_mfma_f32_32x32x16_bf16 v[48:63], v[212:215], v[238:241], v[48:63]
	global_load_dwordx4 v[164:167], v181, s[38:39]
	ds_read_b128 v[204:207], v190 offset:2048
	s_waitcnt lgkmcnt(4)
	v_mfma_f32_32x32x16_bf16 v[96:111], v[208:211], v[242:245], v[96:111]
	global_load_dwordx4 v[168:171], v182, s[38:39]
	ds_read_b128 v[222:225], v250
	v_mfma_f32_32x32x16_bf16 v[32:47], v[212:215], v[242:245], v[32:47]
	global_load_dwordx4 v[172:175], v184, s[38:39]
	ds_read_b128 v[226:229], v250 offset:2048
	s_waitcnt lgkmcnt(5)
	v_mfma_f32_32x32x16_bf16 v[80:95], v[208:211], v[246:249], v[80:95]
	ds_read_b128 v[230:233], v250 offset:4096
	v_mfma_f32_32x32x16_bf16 v[16:31], v[212:215], v[246:249], v[16:31]
	ds_read_b128 v[234:237], v250 offset:6144
	s_waitcnt lgkmcnt(6)
	v_mfma_f32_32x32x16_bf16 v[64:79], v[208:211], v[192:195], v[64:79]
	v_mfma_f32_32x32x16_bf16 v[0:15], v[212:215], v[192:195], v[0:15]
	s_barrier
	v_xad_u32 v191, v187, 64, s41
	v_xad_u32 v251, v189, 64, s41
	s_waitcnt lgkmcnt(3)
	v_mfma_f32_32x32x16_bf16 v[112:127], v[200:203], v[222:225], v[112:127]
	ds_read_b128 v[208:211], v191
	v_mfma_f32_32x32x16_bf16 v[48:63], v[204:207], v[222:225], v[48:63]
	ds_read_b128 v[212:215], v191 offset:2048
	s_waitcnt lgkmcnt(4)
	v_mfma_f32_32x32x16_bf16 v[96:111], v[200:203], v[226:229], v[96:111]
	ds_read_b128 v[238:241], v251
	s_waitcnt vmcnt(11)
	ds_write_b128 v185, v[128:131]
	v_mfma_f32_32x32x16_bf16 v[32:47], v[204:207], v[226:229], v[32:47]
	ds_read_b128 v[242:245], v251 offset:2048
	s_waitcnt vmcnt(10)
	ds_write_b128 v185, v[132:135] offset:2048
	s_waitcnt lgkmcnt(7)
	v_mfma_f32_32x32x16_bf16 v[80:95], v[200:203], v[230:233], v[80:95]
	ds_read_b128 v[246:249], v251 offset:4096
	s_waitcnt vmcnt(9)
	ds_write_b128 v185, v[136:139] offset:4096
	v_mfma_f32_32x32x16_bf16 v[16:31], v[204:207], v[230:233], v[16:31]
	ds_read_b128 v[192:195], v251 offset:6144
	s_waitcnt vmcnt(8)
	ds_write_b128 v185, v[140:143] offset:6144
	s_waitcnt lgkmcnt(10)
	v_mfma_f32_32x32x16_bf16 v[64:79], v[200:203], v[234:237], v[64:79]
	s_waitcnt vmcnt(7)
	ds_write_b128 v185, v[144:147] offset:8192
	v_mfma_f32_32x32x16_bf16 v[0:15], v[204:207], v[234:237], v[0:15]
	s_waitcnt vmcnt(6)
	ds_write_b128 v185, v[148:151] offset:10240
	s_waitcnt lgkmcnt(9)
	v_mfma_f32_32x32x16_bf16 v[112:127], v[208:211], v[238:241], v[112:127]
	s_waitcnt vmcnt(5)
	ds_write_b128 v185, v[152:155] offset:12288
	v_mfma_f32_32x32x16_bf16 v[48:63], v[212:215], v[238:241], v[48:63]
	s_waitcnt vmcnt(4)
	ds_write_b128 v185, v[156:159] offset:14336
	s_waitcnt lgkmcnt(9)
	v_mfma_f32_32x32x16_bf16 v[96:111], v[208:211], v[242:245], v[96:111]
	s_waitcnt vmcnt(3)
	ds_write_b128 v185, v[160:163] offset:16384
	v_mfma_f32_32x32x16_bf16 v[32:47], v[212:215], v[242:245], v[32:47]
	s_waitcnt vmcnt(2)
	ds_write_b128 v185, v[164:167] offset:18432
	s_waitcnt lgkmcnt(9)
	v_mfma_f32_32x32x16_bf16 v[80:95], v[208:211], v[246:249], v[80:95]
	s_waitcnt vmcnt(1)
	ds_write_b128 v185, v[168:171] offset:20480
	v_mfma_f32_32x32x16_bf16 v[16:31], v[212:215], v[246:249], v[16:31]
	s_waitcnt vmcnt(0)
	ds_write_b128 v185, v[172:175] offset:22528
	s_waitcnt lgkmcnt(9)
	v_mfma_f32_32x32x16_bf16 v[64:79], v[208:211], v[192:195], v[64:79]
	v_mfma_f32_32x32x16_bf16 v[0:15], v[212:215], v[192:195], v[0:15]
	s_add_u32 s28, s28, 0x80
	s_addc_u32 s29, s29, 0
	s_add_u32 s38, s38, 0x80
	s_addc_u32 s39, s39, 0
	s_sub_i32 s40, s40, 0x6000
	s_cmp_lt_i32 s40, 0
	s_cselect_b32 s42, 0x12000, 0
	s_add_i32 s40, s40, s42
	s_sub_i32 s41, s41, 0x6000
	s_cmp_lt_i32 s41, 0
	s_cselect_b32 s42, 0x12000, 0
	s_add_i32 s41, s41, s42
	v_subrev_u32_e32 v196, 0x6000, v185
	v_add_u32_e32 v198, 0xc000, v185
	v_min_u32_e32 v185, v196, v198
	s_add_i32 s7, s7, 1
	s_cmp_lt_u32 s7, 63
	s_waitcnt lgkmcnt(0)
	s_barrier
	s_cbranch_scc1 .Lg6_loop
	v_add_u32_e32 v190, s40, v186
	v_add_u32_e32 v191, s40, v187
	v_add_u32_e32 v250, s40, v188
	v_add_u32_e32 v251, s40, v189
	ds_read_b128 v[200:203], v190
	ds_read_b128 v[204:207], v190 offset:2048
	ds_read_b128 v[222:225], v250
	ds_read_b128 v[226:229], v250 offset:2048
	ds_read_b128 v[230:233], v250 offset:4096
	ds_read_b128 v[234:237], v250 offset:6144
	s_waitcnt lgkmcnt(3)
	v_mfma_f32_32x32x16_bf16 v[112:127], v[200:203], v[222:225], v[112:127]
	ds_read_b128 v[208:211], v191
	v_mfma_f32_32x32x16_bf16 v[48:63], v[204:207], v[222:225], v[48:63]
	ds_read_b128 v[212:215], v191 offset:2048
	s_waitcnt lgkmcnt(4)
	v_mfma_f32_32x32x16_bf16 v[96:111], v[200:203], v[226:229], v[96:111]
	ds_read_b128 v[238:241], v251
	v_mfma_f32_32x32x16_bf16 v[32:47], v[204:207], v[226:229], v[32:47]
	ds_read_b128 v[242:245], v251 offset:2048
	s_waitcnt lgkmcnt(5)
	v_mfma_f32_32x32x16_bf16 v[80:95], v[200:203], v[230:233], v[80:95]
	ds_read_b128 v[246:249], v251 offset:4096
	v_mfma_f32_32x32x16_bf16 v[16:31], v[204:207], v[230:233], v[16:31]
	ds_read_b128 v[192:195], v251 offset:6144
	s_waitcnt lgkmcnt(6)
	v_mfma_f32_32x32x16_bf16 v[64:79], v[200:203], v[234:237], v[64:79]
	v_mfma_f32_32x32x16_bf16 v[0:15], v[204:207], v[234:237], v[0:15]
	v_xad_u32 v190, v186, 64, s41
	v_xad_u32 v250, v188, 64, s41
	s_waitcnt lgkmcnt(3)
	v_mfma_f32_32x32x16_bf16 v[112:127], v[208:211], v[238:241], v[112:127]
	ds_read_b128 v[200:203], v190
	v_mfma_f32_32x32x16_bf16 v[48:63], v[212:215], v[238:241], v[48:63]
	ds_read_b128 v[204:207], v190 offset:2048
	s_waitcnt lgkmcnt(4)
	v_mfma_f32_32x32x16_bf16 v[96:111], v[208:211], v[242:245], v[96:111]
	ds_read_b128 v[222:225], v250
	v_mfma_f32_32x32x16_bf16 v[32:47], v[212:215], v[242:245], v[32:47]
	ds_read_b128 v[226:229], v250 offset:2048
	s_waitcnt lgkmcnt(5)
	v_mfma_f32_32x32x16_bf16 v[80:95], v[208:211], v[246:249], v[80:95]
	ds_read_b128 v[230:233], v250 offset:4096
	v_mfma_f32_32x32x16_bf16 v[16:31], v[212:215], v[246:249], v[16:31]
	ds_read_b128 v[234:237], v250 offset:6144
	s_waitcnt lgkmcnt(6)
	v_mfma_f32_32x32x16_bf16 v[64:79], v[208:211], v[192:195], v[64:79]
	v_mfma_f32_32x32x16_bf16 v[0:15], v[212:215], v[192:195], v[0:15]
	v_xad_u32 v191, v187, 64, s41
	v_xad_u32 v251, v189, 64, s41
	s_waitcnt lgkmcnt(3)
	v_mfma_f32_32x32x16_bf16 v[112:127], v[200:203], v[222:225], v[112:127]
	ds_read_b128 v[208:211], v191
	v_mfma_f32_32x32x16_bf16 v[48:63], v[204:207], v[222:225], v[48:63]
	ds_read_b128 v[212:215], v191 offset:2048
	s_waitcnt lgkmcnt(4)
	v_mfma_f32_32x32x16_bf16 v[96:111], v[200:203], v[226:229], v[96:111]
	ds_read_b128 v[238:241], v251
	v_mfma_f32_32x32x16_bf16 v[32:47], v[204:207], v[226:229], v[32:47]
	ds_read_b128 v[242:245], v251 offset:2048
	s_waitcnt lgkmcnt(5)
	v_mfma_f32_32x32x16_bf16 v[80:95], v[200:203], v[230:233], v[80:95]
	ds_read_b128 v[246:249], v251 offset:4096
	v_mfma_f32_32x32x16_bf16 v[16:31], v[204:207], v[230:233], v[16:31]
	ds_read_b128 v[192:195], v251 offset:6144
	s_waitcnt lgkmcnt(6)
	v_mfma_f32_32x32x16_bf16 v[64:79], v[200:203], v[234:237], v[64:79]
	v_mfma_f32_32x32x16_bf16 v[0:15], v[204:207], v[234:237], v[0:15]
	s_waitcnt lgkmcnt(3)
	v_mfma_f32_32x32x16_bf16 v[112:127], v[208:211], v[238:241], v[112:127]
	v_mfma_f32_32x32x16_bf16 v[48:63], v[212:215], v[238:241], v[48:63]
	s_waitcnt lgkmcnt(2)
	v_mfma_f32_32x32x16_bf16 v[96:111], v[208:211], v[242:245], v[96:111]
	v_mfma_f32_32x32x16_bf16 v[32:47], v[212:215], v[242:245], v[32:47]
	s_waitcnt lgkmcnt(1)
	v_mfma_f32_32x32x16_bf16 v[80:95], v[208:211], v[246:249], v[80:95]
	v_mfma_f32_32x32x16_bf16 v[16:31], v[212:215], v[246:249], v[16:31]
	s_waitcnt lgkmcnt(0)
	v_mfma_f32_32x32x16_bf16 v[64:79], v[208:211], v[192:195], v[64:79]
	v_mfma_f32_32x32x16_bf16 v[0:15], v[212:215], v[192:195], v[0:15]
	s_setprio 0
	s_nop 7
	s_nop 7

.LBB0_630:
	s_or_b64 exec, exec, s[36:37]
	s_lshl_b32 s6, s68, 7
	v_mov_b32_e32 v64, v197
	s_and_b32 s93, s6, 0x380
	s_lshl_b64 s[6:7], s[0:1], 10
	s_add_u32 s6, s80, s6
	v_and_b32_e32 v49, 7, v64
	v_ashrrev_i32_e32 v48, 3, v64
	v_lshlrev_b32_e32 v0, 3, v49
	s_addc_u32 s7, s81, s7
	s_lshl_b32 s8, s93, 9
	v_lshl_or_b32 v198, v48, 8, v0
	s_add_u32 s8, s4, s8
	v_lshl_add_u64 v[160:161], v[198:199], 2, s[6:7]
	s_addc_u32 s9, s5, 0
	v_add_co_u32_e32 v164, vcc, s35, v160
	v_lshl_add_u64 v[162:163], v[198:199], 1, s[8:9]
	s_nop 0
	v_addc_co_u32_e32 v165, vcc, 0, v161, vcc
	v_add_co_u32_e32 v166, vcc, s94, v162
	s_mov_b32 s36, 0x10000
	s_nop 0
	v_addc_co_u32_e32 v167, vcc, 0, v163, vcc
	v_add_co_u32_e32 v168, vcc, s36, v160
	s_mov_b64 s[6:7], 0x8000
	s_nop 0
	v_addc_co_u32_e32 v169, vcc, 0, v161, vcc
	v_lshl_add_u64 v[24:25], v[160:161], 0, s[6:7]
	s_mov_b64 s[6:7], 0x18000
	v_add_co_u32_e32 v170, vcc, s35, v162
	v_lshl_add_u64 v[40:41], v[160:161], 0, s[6:7]
	s_nop 0
	v_addc_co_u32_e32 v171, vcc, 0, v163, vcc
	s_mov_b32 s6, 0x18000
	s_mov_b64 s[40:41], 0x10000
	v_add_co_u32_e32 v172, vcc, s6, v160
	v_lshl_add_u64 v[28:29], v[160:161], 0, s[40:41]
	global_load_dwordx4 v[0:3], v[160:161], off offset:16
	global_load_dwordx4 v[4:7], v[160:161], off
	global_load_dwordx4 v[8:11], v[162:163], off
	global_load_dwordx4 v[12:15], v[164:165], off
	v_addc_co_u32_e32 v173, vcc, 0, v161, vcc
	global_load_dwordx4 v[16:19], v[166:167], off
	global_load_dwordx4 v[20:23], v[168:169], off
	s_nop 0
	global_load_dwordx4 v[24:27], v[24:25], off offset:16
	s_nop 0
	global_load_dwordx4 v[28:31], v[28:29], off offset:16
	v_add_co_u32_e32 v174, vcc, s95, v162
	global_load_dwordx4 v[32:35], v[170:171], off
	global_load_dwordx4 v[36:39], v[172:173], off
	s_nop 0
	global_load_dwordx4 v[40:43], v[40:41], off offset:16
	v_addc_co_u32_e32 v175, vcc, 0, v163, vcc
	global_load_dwordx4 v[44:47], v[174:175], off
	v_mul_lo_u32 v48, v48, s97
	v_lshlrev_b32_e32 v49, 4, v49
	s_mov_b64 s[6:7], 0x8100
	v_add3_u32 v178, v48, v49, 0
	v_lshl_add_u64 v[48:49], v[160:161], 0, s[6:7]
	s_mov_b64 s[6:7], 0x10100
	v_lshl_add_u64 v[50:51], v[160:161], 0, s[6:7]
	s_mov_b64 s[6:7], 0x18100
	v_lshl_add_u64 v[52:53], v[160:161], 0, s[6:7]
	global_load_dwordx4 v[148:151], v[160:161], off offset:272
	global_load_dwordx4 v[156:159], v[160:161], off offset:256
	global_load_dwordx4 v[144:147], v[162:163], off offset:128
	global_load_dwordx4 v[136:139], v[164:165], off offset:256
	global_load_dwordx4 v[140:143], v[48:49], off offset:16
	global_load_dwordx4 v[124:127], v[168:169], off offset:256
	global_load_dwordx4 v[112:115], v[172:173], off offset:256
	global_load_dwordx4 v[128:131], v[50:51], off offset:16
	global_load_dwordx4 v[116:119], v[52:53], off offset:16
	global_load_dwordx4 v[152:155], v[166:167], off offset:128
	global_load_dwordx4 v[132:135], v[170:171], off offset:128
	global_load_dwordx4 v[120:123], v[174:175], off offset:128
	s_mov_b64 s[6:7], 0x18200
	v_add_u32_e32 v179, 0xd800, v178
	s_waitcnt vmcnt(22)
	v_cvt_pk_bf16_f32 v4, v4, v5
	v_cvt_pk_bf16_f32 v5, v6, v7
	v_cvt_pk_bf16_f32 v6, v0, v1
	v_cvt_pk_bf16_f32 v7, v2, v3
	s_waitcnt vmcnt(20)
	v_cvt_pk_bf16_f32 v0, v12, v13
	v_cvt_pk_bf16_f32 v1, v14, v15
	s_waitcnt vmcnt(17)
	v_cvt_pk_bf16_f32 v2, v24, v25
	v_cvt_pk_bf16_f32 v3, v26, v27
	ds_write_b128 v178, v[4:7]
	ds_write_b128 v178, v[8:11] offset:18432
	v_cvt_pk_bf16_f32 v4, v20, v21
	v_cvt_pk_bf16_f32 v5, v22, v23
	s_waitcnt vmcnt(16)
	v_cvt_pk_bf16_f32 v6, v28, v29
	v_cvt_pk_bf16_f32 v7, v30, v31
	ds_write_b128 v178, v[0:3] offset:4608
	ds_write_b128 v178, v[16:19] offset:23040
	ds_write_b128 v178, v[4:7] offset:9216
	s_waitcnt vmcnt(15)
	ds_write_b128 v178, v[32:35] offset:27648
	s_waitcnt vmcnt(14)
	v_cvt_pk_bf16_f32 v0, v36, v37
	v_cvt_pk_bf16_f32 v1, v38, v39
	s_waitcnt vmcnt(13)
	v_cvt_pk_bf16_f32 v2, v40, v41
	v_cvt_pk_bf16_f32 v3, v42, v43
	ds_write_b128 v178, v[0:3] offset:13824
	s_waitcnt vmcnt(12)
	ds_write_b128 v178, v[44:47] offset:32256
	v_lshl_add_u64 v[0:1], v[160:161], 0, s[6:7]
	s_mov_b64 s[6:7], 0x10200
	v_lshl_add_u64 v[2:3], v[160:161], 0, s[6:7]
	s_mov_b64 s[6:7], 0x8200
	s_waitcnt lgkmcnt(0)
	s_barrier
	v_lshl_add_u64 v[4:5], v[160:161], 0, s[6:7]
	global_load_dwordx4 v[104:107], v[160:161], off offset:528
	global_load_dwordx4 v[108:111], v[160:161], off offset:512
	global_load_dwordx4 v[100:103], v[162:163], off offset:256
	global_load_dwordx4 v[96:99], v[164:165], off offset:512
	global_load_dwordx4 v[60:63], v[4:5], off offset:16
	global_load_dwordx4 v[52:55], v[166:167], off offset:256
	global_load_dwordx4 v[48:51], v[168:169], off offset:512
	global_load_dwordx4 v[44:47], v[170:171], off offset:256
	global_load_dwordx4 v[36:39], v[172:173], off offset:512
	global_load_dwordx4 v[56:59], v[2:3], off offset:16
	global_load_dwordx4 v[40:43], v[0:1], off offset:16
	global_load_dwordx4 v[32:35], v[174:175], off offset:256
	v_readfirstlane_b32 s6, v64
	s_lshr_b32 s7, s6, 1
	v_and_b32_e32 v0, 31, v64
	s_and_b32 s7, s7, 0xfffffc0
	v_or_b32_e32 v1, s7, v0
	v_and_or_b32 v0, s6, 64, v0
	s_mov_b64 s[6:7], 0x8300
	v_lshrrev_b32_e32 v2, 1, v64
	v_lshl_add_u64 v[194:195], v[160:161], 0, s[6:7]
	s_mov_b64 s[6:7], 0x10300
	v_mul_lo_u32 v1, v1, s97
	v_and_b32_e32 v2, 16, v2
	v_lshl_add_u64 v[200:201], v[160:161], 0, s[6:7]
	s_mov_b64 s[6:7], 0x18300
	v_mul_u32_u24_e32 v0, 0x90, v0
	v_add3_u32 v176, v1, v2, 0
	v_lshl_add_u64 v[202:203], v[160:161], 0, s[6:7]
	v_add3_u32 v177, v0, v2, 0
	s_setprio 1
	ds_read_b128 v[0:3], v176
	ds_read_b128 v[4:7], v177 offset:18432
	ds_read_b128 v[8:11], v177 offset:23040
	s_waitcnt lgkmcnt(1)
	v_mfma_f32_32x32x16_bf16 v[80:95], v[0:3], v[4:7], 0
	s_waitcnt lgkmcnt(0)
	v_mfma_f32_32x32x16_bf16 v[64:79], v[0:3], v[8:11], 0
	ds_read_b128 v[0:3], v176 offset:4608
	ds_read_b128 v[180:183], v176 offset:32
	ds_read_b128 v[184:187], v177 offset:18464
	ds_read_b128 v[188:191], v177 offset:23072
	s_waitcnt lgkmcnt(1)
	v_mfma_f32_32x32x16_bf16 v[80:95], v[180:183], v[184:187], v[80:95]
	s_waitcnt lgkmcnt(0)
	v_mfma_f32_32x32x16_bf16 v[64:79], v[180:183], v[188:191], v[64:79]
	ds_read_b128 v[180:183], v176 offset:4640
	v_mfma_f32_32x32x16_bf16 v[16:31], v[0:3], v[4:7], 0
	v_mfma_f32_32x32x16_bf16 v[0:15], v[0:3], v[8:11], 0
	s_waitcnt lgkmcnt(0)
	v_mfma_f32_32x32x16_bf16 v[16:31], v[180:183], v[184:187], v[16:31]
	v_mfma_f32_32x32x16_bf16 v[0:15], v[180:183], v[188:191], v[0:15]
	ds_read_b128 v[180:183], v176 offset:64
	ds_read_b128 v[184:187], v177 offset:18496
	ds_read_b128 v[188:191], v177 offset:23104
	s_waitcnt lgkmcnt(1)
	v_mfma_f32_32x32x16_bf16 v[80:95], v[180:183], v[184:187], v[80:95]
	s_waitcnt lgkmcnt(0)
	v_mfma_f32_32x32x16_bf16 v[64:79], v[180:183], v[188:191], v[64:79]
	ds_read_b128 v[180:183], v176 offset:4672
	s_waitcnt lgkmcnt(0)
	v_mfma_f32_32x32x16_bf16 v[16:31], v[180:183], v[184:187], v[16:31]
	v_mfma_f32_32x32x16_bf16 v[0:15], v[180:183], v[188:191], v[0:15]
	ds_read_b128 v[180:183], v176 offset:96
	ds_read_b128 v[184:187], v177 offset:18528
	ds_read_b128 v[188:191], v177 offset:23136
	s_waitcnt lgkmcnt(1)
	v_mfma_f32_32x32x16_bf16 v[80:95], v[180:183], v[184:187], v[80:95]
	s_waitcnt lgkmcnt(0)
	v_mfma_f32_32x32x16_bf16 v[64:79], v[180:183], v[188:191], v[64:79]
	ds_read_b128 v[180:183], v176 offset:4704
	s_waitcnt lgkmcnt(0)
	v_mfma_f32_32x32x16_bf16 v[16:31], v[180:183], v[184:187], v[16:31]
	v_mfma_f32_32x32x16_bf16 v[0:15], v[180:183], v[188:191], v[0:15]
	s_setprio 0
	s_waitcnt vmcnt(22)
	v_cvt_pk_bf16_f32 v156, v156, v157
	v_cvt_pk_bf16_f32 v157, v158, v159
	v_cvt_pk_bf16_f32 v158, v148, v149
	v_cvt_pk_bf16_f32 v159, v150, v151
	s_waitcnt vmcnt(20)
	v_cvt_pk_bf16_f32 v136, v136, v137
	v_cvt_pk_bf16_f32 v137, v138, v139
	s_waitcnt vmcnt(19)
	v_cvt_pk_bf16_f32 v138, v140, v141
	v_cvt_pk_bf16_f32 v139, v142, v143
	s_waitcnt vmcnt(18)
	v_cvt_pk_bf16_f32 v124, v124, v125
	v_cvt_pk_bf16_f32 v125, v126, v127
	s_waitcnt vmcnt(16)
	v_cvt_pk_bf16_f32 v126, v128, v129
	v_cvt_pk_bf16_f32 v127, v130, v131
	v_cvt_pk_bf16_f32 v112, v112, v113
	v_cvt_pk_bf16_f32 v113, v114, v115
	s_waitcnt vmcnt(15)
	v_cvt_pk_bf16_f32 v114, v116, v117
	v_cvt_pk_bf16_f32 v115, v118, v119
	ds_write_b128 v178, v[156:159] offset:36864
	ds_write_b128 v178, v[144:147] offset:55296
	ds_write_b128 v178, v[136:139] offset:41472
	s_waitcnt vmcnt(14)
	ds_write_b128 v178, v[152:155] offset:59904
	ds_write_b128 v178, v[124:127] offset:46080
	s_waitcnt vmcnt(13)
	ds_write_b128 v178, v[132:135] offset:64512
	ds_write_b128 v178, v[112:115] offset:50688
	s_waitcnt vmcnt(12)
	ds_write_b128 v179, v[120:123] offset:13824
	s_waitcnt lgkmcnt(0)
	s_barrier
	global_load_dwordx4 v[148:151], v[160:161], off offset:784
	global_load_dwordx4 v[152:155], v[160:161], off offset:768
	global_load_dwordx4 v[140:143], v[162:163], off offset:384
	global_load_dwordx4 v[136:139], v[166:167], off offset:384
	global_load_dwordx4 v[128:131], v[168:169], off offset:768
	global_load_dwordx4 v[144:147], v[194:195], off offset:16
	global_load_dwordx4 v[132:135], v[200:201], off offset:16
	global_load_dwordx4 v[124:127], v[170:171], off offset:384
	global_load_dwordx4 v[116:119], v[172:173], off offset:768
	global_load_dwordx4 v[156:159], v[164:165], off offset:768
	global_load_dwordx4 v[120:123], v[202:203], off offset:16
	global_load_dwordx4 v[112:115], v[174:175], off offset:384
	s_setprio 1
	ds_read_b128 v[160:163], v176 offset:36864
	ds_read_b128 v[164:167], v177 offset:55296
	ds_read_b128 v[168:171], v177 offset:59904
	s_waitcnt lgkmcnt(1)
	v_mfma_f32_32x32x16_bf16 v[80:95], v[160:163], v[164:167], v[80:95]
	s_waitcnt lgkmcnt(0)
	v_mfma_f32_32x32x16_bf16 v[64:79], v[160:163], v[168:171], v[64:79]
	ds_read_b128 v[160:163], v176 offset:41472
	s_waitcnt lgkmcnt(0)
	v_mfma_f32_32x32x16_bf16 v[16:31], v[160:163], v[164:167], v[16:31]
	v_mfma_f32_32x32x16_bf16 v[0:15], v[160:163], v[168:171], v[0:15]
	ds_read_b128 v[160:163], v176 offset:36896
	ds_read_b128 v[164:167], v177 offset:55328
	ds_read_b128 v[168:171], v177 offset:59936
	s_waitcnt lgkmcnt(1)
	v_mfma_f32_32x32x16_bf16 v[80:95], v[160:163], v[164:167], v[80:95]
	s_waitcnt lgkmcnt(0)
	v_mfma_f32_32x32x16_bf16 v[64:79], v[160:163], v[168:171], v[64:79]
	ds_read_b128 v[160:163], v176 offset:41504
	s_waitcnt lgkmcnt(0)
	v_mfma_f32_32x32x16_bf16 v[16:31], v[160:163], v[164:167], v[16:31]
	v_mfma_f32_32x32x16_bf16 v[0:15], v[160:163], v[168:171], v[0:15]
	ds_read_b128 v[160:163], v176 offset:36928
	ds_read_b128 v[164:167], v177 offset:55360
	ds_read_b128 v[168:171], v177 offset:59968
	s_waitcnt lgkmcnt(1)
	v_mfma_f32_32x32x16_bf16 v[80:95], v[160:163], v[164:167], v[80:95]
	s_waitcnt lgkmcnt(0)
	v_mfma_f32_32x32x16_bf16 v[64:79], v[160:163], v[168:171], v[64:79]
	ds_read_b128 v[160:163], v176 offset:41536
	s_waitcnt lgkmcnt(0)
	v_mfma_f32_32x32x16_bf16 v[16:31], v[160:163], v[164:167], v[16:31]
	v_mfma_f32_32x32x16_bf16 v[0:15], v[160:163], v[168:171], v[0:15]
	ds_read_b128 v[160:163], v176 offset:36960
	ds_read_b128 v[164:167], v177 offset:55392
	ds_read_b128 v[168:171], v177 offset:60000
	s_waitcnt lgkmcnt(1)
	v_mfma_f32_32x32x16_bf16 v[80:95], v[160:163], v[164:167], v[80:95]
	s_waitcnt lgkmcnt(0)
	v_mfma_f32_32x32x16_bf16 v[64:79], v[160:163], v[168:171], v[64:79]
	ds_read_b128 v[160:163], v176 offset:41568
	s_waitcnt lgkmcnt(0)
	v_mfma_f32_32x32x16_bf16 v[16:31], v[160:163], v[164:167], v[16:31]
	v_mfma_f32_32x32x16_bf16 v[0:15], v[160:163], v[168:171], v[0:15]
	s_setprio 0
	s_waitcnt vmcnt(22)
	v_cvt_pk_bf16_f32 v108, v108, v109
	v_cvt_pk_bf16_f32 v109, v110, v111
	v_cvt_pk_bf16_f32 v110, v104, v105
	v_cvt_pk_bf16_f32 v111, v106, v107
	s_waitcnt vmcnt(20)
	v_cvt_pk_bf16_f32 v96, v96, v97
	v_cvt_pk_bf16_f32 v97, v98, v99
	s_waitcnt vmcnt(19)
	v_cvt_pk_bf16_f32 v98, v60, v61
	v_cvt_pk_bf16_f32 v99, v62, v63
	s_waitcnt vmcnt(17)
	v_cvt_pk_bf16_f32 v48, v48, v49
	v_cvt_pk_bf16_f32 v49, v50, v51
	s_waitcnt vmcnt(14)
	v_cvt_pk_bf16_f32 v50, v56, v57
	v_cvt_pk_bf16_f32 v51, v58, v59
	v_cvt_pk_bf16_f32 v36, v36, v37
	v_cvt_pk_bf16_f32 v37, v38, v39
	s_waitcnt vmcnt(13)
	v_cvt_pk_bf16_f32 v38, v40, v41
	v_cvt_pk_bf16_f32 v39, v42, v43
	ds_write_b128 v178, v[108:111]
	ds_write_b128 v178, v[100:103] offset:18432
	ds_write_b128 v178, v[96:99] offset:4608
	ds_write_b128 v178, v[52:55] offset:23040
	ds_write_b128 v178, v[48:51] offset:9216
	ds_write_b128 v178, v[44:47] offset:27648
	ds_write_b128 v178, v[36:39] offset:13824
	s_waitcnt vmcnt(12)
	ds_write_b128 v178, v[32:35] offset:32256
	s_waitcnt lgkmcnt(0)
	s_barrier
	s_setprio 1
	ds_read_b128 v[32:35], v176
	ds_read_b128 v[36:39], v177 offset:18432
	ds_read_b128 v[40:43], v177 offset:23040
	s_waitcnt lgkmcnt(1)
	v_mfma_f32_32x32x16_bf16 v[80:95], v[32:35], v[36:39], v[80:95]
	s_waitcnt lgkmcnt(0)
	v_mfma_f32_32x32x16_bf16 v[64:79], v[32:35], v[40:43], v[64:79]
	ds_read_b128 v[32:35], v176 offset:4608
	s_waitcnt lgkmcnt(0)
	v_mfma_f32_32x32x16_bf16 v[16:31], v[32:35], v[36:39], v[16:31]
	v_mfma_f32_32x32x16_bf16 v[0:15], v[32:35], v[40:43], v[0:15]
	ds_read_b128 v[32:35], v176 offset:32
	ds_read_b128 v[36:39], v177 offset:18464
	ds_read_b128 v[40:43], v177 offset:23072
	s_waitcnt lgkmcnt(1)
	v_mfma_f32_32x32x16_bf16 v[80:95], v[32:35], v[36:39], v[80:95]
	s_waitcnt lgkmcnt(0)
	v_mfma_f32_32x32x16_bf16 v[64:79], v[32:35], v[40:43], v[64:79]
	ds_read_b128 v[32:35], v176 offset:4640
	s_waitcnt lgkmcnt(0)
	v_mfma_f32_32x32x16_bf16 v[16:31], v[32:35], v[36:39], v[16:31]
	v_mfma_f32_32x32x16_bf16 v[0:15], v[32:35], v[40:43], v[0:15]
	ds_read_b128 v[32:35], v176 offset:64
	ds_read_b128 v[36:39], v177 offset:18496
	ds_read_b128 v[40:43], v177 offset:23104
	s_waitcnt lgkmcnt(1)
	v_mfma_f32_32x32x16_bf16 v[80:95], v[32:35], v[36:39], v[80:95]
	s_waitcnt lgkmcnt(0)
	v_mfma_f32_32x32x16_bf16 v[64:79], v[32:35], v[40:43], v[64:79]
	ds_read_b128 v[32:35], v176 offset:4672
	s_waitcnt lgkmcnt(0)
	v_mfma_f32_32x32x16_bf16 v[16:31], v[32:35], v[36:39], v[16:31]
	v_mfma_f32_32x32x16_bf16 v[0:15], v[32:35], v[40:43], v[0:15]
	ds_read_b128 v[32:35], v176 offset:96
	ds_read_b128 v[36:39], v177 offset:18528
	ds_read_b128 v[40:43], v177 offset:23136
	s_waitcnt lgkmcnt(1)
	v_mfma_f32_32x32x16_bf16 v[80:95], v[32:35], v[36:39], v[80:95]
	s_waitcnt lgkmcnt(0)
	v_mfma_f32_32x32x16_bf16 v[64:79], v[32:35], v[40:43], v[64:79]
	ds_read_b128 v[32:35], v176 offset:4704
	s_waitcnt lgkmcnt(0)
	v_mfma_f32_32x32x16_bf16 v[16:31], v[32:35], v[36:39], v[16:31]
	v_mfma_f32_32x32x16_bf16 v[0:15], v[32:35], v[40:43], v[0:15]
	s_setprio 0
	s_waitcnt vmcnt(10)
	v_cvt_pk_bf16_f32 v32, v152, v153
	v_cvt_pk_bf16_f32 v33, v154, v155
	v_cvt_pk_bf16_f32 v34, v148, v149
	v_cvt_pk_bf16_f32 v35, v150, v151
	ds_write_b128 v178, v[32:35] offset:36864
	s_waitcnt vmcnt(9)
	ds_write_b128 v178, v[140:143] offset:55296
	s_waitcnt vmcnt(2)
	v_cvt_pk_bf16_f32 v32, v156, v157
	v_cvt_pk_bf16_f32 v33, v158, v159
	v_cvt_pk_bf16_f32 v34, v144, v145
	v_cvt_pk_bf16_f32 v35, v146, v147
	ds_write_b128 v178, v[32:35] offset:41472
	ds_write_b128 v178, v[136:139] offset:59904
	v_cvt_pk_bf16_f32 v32, v128, v129
	v_cvt_pk_bf16_f32 v33, v130, v131
	v_cvt_pk_bf16_f32 v34, v132, v133
	v_cvt_pk_bf16_f32 v35, v134, v135
	ds_write_b128 v178, v[32:35] offset:46080
	ds_write_b128 v178, v[124:127] offset:64512
	v_cvt_pk_bf16_f32 v32, v116, v117
	v_cvt_pk_bf16_f32 v33, v118, v119
	s_waitcnt vmcnt(1)
	v_cvt_pk_bf16_f32 v34, v120, v121
	v_cvt_pk_bf16_f32 v35, v122, v123
	ds_write_b128 v178, v[32:35] offset:50688
	s_waitcnt vmcnt(0)
	ds_write_b128 v179, v[112:115] offset:13824
	s_waitcnt lgkmcnt(0)
	s_barrier
	s_setprio 1
	ds_read_b128 v[32:35], v176 offset:36864
	ds_read_b128 v[36:39], v177 offset:55296
	ds_read_b128 v[40:43], v177 offset:59904
	s_waitcnt lgkmcnt(1)
	v_mfma_f32_32x32x16_bf16 v[80:95], v[32:35], v[36:39], v[80:95]
	s_waitcnt lgkmcnt(0)
	v_mfma_f32_32x32x16_bf16 v[64:79], v[32:35], v[40:43], v[64:79]
	ds_read_b128 v[32:35], v176 offset:41472
	s_waitcnt lgkmcnt(0)
	v_mfma_f32_32x32x16_bf16 v[16:31], v[32:35], v[36:39], v[16:31]
	v_mfma_f32_32x32x16_bf16 v[0:15], v[32:35], v[40:43], v[0:15]
	ds_read_b128 v[32:35], v176 offset:36896
	ds_read_b128 v[36:39], v177 offset:55328
	ds_read_b128 v[40:43], v177 offset:59936
	s_waitcnt lgkmcnt(1)
	v_mfma_f32_32x32x16_bf16 v[80:95], v[32:35], v[36:39], v[80:95]
	s_waitcnt lgkmcnt(0)
	v_mfma_f32_32x32x16_bf16 v[64:79], v[32:35], v[40:43], v[64:79]
	ds_read_b128 v[32:35], v176 offset:41504
	s_waitcnt lgkmcnt(0)
	v_mfma_f32_32x32x16_bf16 v[16:31], v[32:35], v[36:39], v[16:31]
	v_mfma_f32_32x32x16_bf16 v[0:15], v[32:35], v[40:43], v[0:15]
	ds_read_b128 v[32:35], v176 offset:36928
	ds_read_b128 v[36:39], v177 offset:55360
	ds_read_b128 v[40:43], v177 offset:59968
	s_waitcnt lgkmcnt(1)
	v_mfma_f32_32x32x16_bf16 v[80:95], v[32:35], v[36:39], v[80:95]
	s_waitcnt lgkmcnt(0)
	v_mfma_f32_32x32x16_bf16 v[64:79], v[32:35], v[40:43], v[64:79]
	ds_read_b128 v[32:35], v176 offset:41536
	s_waitcnt lgkmcnt(0)
	v_mfma_f32_32x32x16_bf16 v[16:31], v[32:35], v[36:39], v[16:31]
	v_mfma_f32_32x32x16_bf16 v[0:15], v[32:35], v[40:43], v[0:15]
	ds_read_b128 v[32:35], v176 offset:36960
	ds_read_b128 v[36:39], v177 offset:55392
	ds_read_b128 v[40:43], v177 offset:60000
	s_waitcnt lgkmcnt(1)
	v_mfma_f32_32x32x16_bf16 v[80:95], v[32:35], v[36:39], v[80:95]
	s_waitcnt lgkmcnt(0)
	v_mfma_f32_32x32x16_bf16 v[64:79], v[32:35], v[40:43], v[64:79]
	ds_read_b128 v[32:35], v176 offset:41568
	s_waitcnt lgkmcnt(0)
	v_mfma_f32_32x32x16_bf16 v[16:31], v[32:35], v[36:39], v[16:31]
	v_mfma_f32_32x32x16_bf16 v[0:15], v[32:35], v[40:43], v[0:15]
	s_setprio 0
	v_mov_b32_e32 v108, v197
	s_barrier
	s_lshl_b64 s[6:7], s[0:1], 11
	s_add_u32 s6, s66, s6
	s_addc_u32 s7, s67, s7
	s_lshl_b32 s101, s93, 11
	s_add_u32 s8, s2, s101
	s_addc_u32 s9, s3, 0
	v_lshrrev_b32_e32 v213, 3, v197
	v_and_b32_e32 v214, 7, v197
	v_lshlrev_b32_e32 v200, 11, v213
	v_lshl_or_b32 v200, v214, 4, v200
	v_add_u32_e32 v201, 0x10000, v200
	v_add_u32_e32 v202, 0x20000, v200
	v_add_u32_e32 v203, 0x30000, v200
	global_load_dwordx4 v[128:131], v200, s[6:7]
	global_load_dwordx4 v[132:135], v201, s[6:7]
	global_load_dwordx4 v[136:139], v202, s[6:7]
	global_load_dwordx4 v[140:143], v203, s[6:7]
	global_load_dwordx4 v[144:147], v200, s[8:9]
	global_load_dwordx4 v[148:151], v201, s[8:9]
	global_load_dwordx4 v[152:155], v202, s[8:9]
	global_load_dwordx4 v[156:159], v203, s[8:9]
	s_add_u32 s6, s6, 0x80
	s_addc_u32 s7, s7, 0
	s_add_u32 s8, s8, 0x80
	s_addc_u32 s9, s9, 0
	v_bfe_u32 v215, v197, 5, 2
	v_and_b32_e32 v198, 3, v214
	v_xor_b32_e32 v198, v198, v215
	v_lshlrev_b32_e32 v198, 4, v198
	v_lshl_or_b32 v204, v213, 6, v198
	v_lshrrev_b32_e32 v215, 2, v214
	v_lshlrev_b32_e32 v198, 6, v215
	v_xor_b32_e32 v204, v204, v198
	v_mul_u32_u24_e32 v215, 0x4000, v215
	v_add_u32_e32 v204, v204, v215
	v_and_b32_e32 v213, 31, v197
	v_bfe_u32 v214, v197, 5, 1
	v_bfe_u32 v215, v197, 2, 2
	v_xor_b32_e32 v198, v214, v215
	v_xor_b32_e32 v222, 2, v198
	v_lshrrev_b32_e32 v214, 7, v197
	v_lshl_or_b32 v214, v214, 6, v213
	v_lshlrev_b32_e32 v214, 6, v214
	v_lshl_or_b32 v205, v198, 4, v214
	v_lshl_or_b32 v206, v222, 4, v214
	v_bfe_u32 v214, v197, 6, 1
	v_mul_u32_u24_e32 v214, 64, v214
	v_add_u32_e32 v214, v214, v213
	v_lshlrev_b32_e32 v214, 6, v214
	v_add_u32_e32 v214, 0x2000, v214
	v_lshl_or_b32 v207, v198, 4, v214
	v_lshl_or_b32 v208, v222, 4, v214
	v_mov_b64_e32 v[32:33], 0
	v_mov_b64_e32 v[34:35], 0
	v_mov_b64_e32 v[36:37], 0
	v_mov_b64_e32 v[38:39], 0
	v_mov_b64_e32 v[40:41], 0
	v_mov_b64_e32 v[42:43], 0
	v_mov_b64_e32 v[44:45], 0
	v_mov_b64_e32 v[46:47], 0
	v_mov_b64_e32 v[48:49], 0
	v_mov_b64_e32 v[50:51], 0
	v_mov_b64_e32 v[52:53], 0
	v_mov_b64_e32 v[54:55], 0
	v_mov_b64_e32 v[56:57], 0
	v_mov_b64_e32 v[58:59], 0
	v_mov_b64_e32 v[60:61], 0
	v_mov_b64_e32 v[62:63], 0
	v_mov_b64_e32 v[96:97], 0
	v_mov_b64_e32 v[98:99], 0
	v_mov_b64_e32 v[100:101], 0
	v_mov_b64_e32 v[102:103], 0
	v_mov_b64_e32 v[104:105], 0
	v_mov_b64_e32 v[106:107], 0
	v_mov_b64_e32 v[108:109], 0
	v_mov_b64_e32 v[110:111], 0
	v_mov_b64_e32 v[112:113], 0
	v_mov_b64_e32 v[114:115], 0
	v_mov_b64_e32 v[116:117], 0
	v_mov_b64_e32 v[118:119], 0
	v_mov_b64_e32 v[120:121], 0
	v_mov_b64_e32 v[122:123], 0
	v_mov_b64_e32 v[124:125], 0
	v_mov_b64_e32 v[126:127], 0
	s_mov_b32 s98, 0
	s_mov_b32 s99, 0x4000
	s_mov_b32 s100, 0
	s_waitcnt vmcnt(7)
	ds_write_b128 v204, v[128:131]
	s_waitcnt vmcnt(6)
	ds_write_b128 v204, v[132:135] offset:2048
	s_waitcnt vmcnt(5)
	ds_write_b128 v204, v[136:139] offset:4096
	s_waitcnt vmcnt(4)
	ds_write_b128 v204, v[140:143] offset:6144
	s_waitcnt vmcnt(3)
	ds_write_b128 v204, v[144:147] offset:8192
	s_waitcnt vmcnt(2)
	ds_write_b128 v204, v[148:151] offset:10240
	s_waitcnt vmcnt(1)
	ds_write_b128 v204, v[152:155] offset:12288
	s_waitcnt vmcnt(0)
	ds_write_b128 v204, v[156:159] offset:14336
	v_subrev_u32_e32 v213, 0x4000, v204
	v_add_u32_e32 v214, 0x8000, v204
	v_min_u32_e32 v204, v213, v214
	s_waitcnt lgkmcnt(0)
	s_barrier
	s_getreg_b32 s101, hwreg(HW_REG_HW_ID, 0, 4)
	s_bitcmp1_b32 s101, 0
	s_cbranch_scc0 .Lg7_noraise
	s_setprio 1
.Lg7_noraise:
.Lg7_loop:
	v_add_u32_e32 v209, s98, v205
	v_add_u32_e32 v210, s98, v206
	v_add_u32_e32 v211, s98, v207
	v_add_u32_e32 v212, s98, v208
	ds_read_b128 v[160:163], v209
	ds_read_b128 v[164:167], v209 offset:2048
	ds_read_b128 v[168:171], v211
	ds_read_b128 v[172:175], v211 offset:2048
	s_waitcnt lgkmcnt(1)
	v_mfma_f32_32x32x16_bf16 v[112:127], v[160:163], v[168:171], v[112:127]
	global_load_dwordx4 v[128:131], v200, s[6:7]
	ds_read_b128 v[176:179], v210
	v_mfma_f32_32x32x16_bf16 v[48:63], v[164:167], v[168:171], v[48:63]
	global_load_dwordx4 v[132:135], v201, s[6:7]
	ds_read_b128 v[180:183], v210 offset:2048
	s_waitcnt lgkmcnt(2)
	v_mfma_f32_32x32x16_bf16 v[96:111], v[160:163], v[172:175], v[96:111]
	global_load_dwordx4 v[136:139], v202, s[6:7]
	ds_read_b128 v[184:187], v212
	v_mfma_f32_32x32x16_bf16 v[32:47], v[164:167], v[172:175], v[32:47]
	global_load_dwordx4 v[140:143], v203, s[6:7]
	ds_read_b128 v[188:191], v212 offset:2048
	v_xad_u32 v209, v205, 64, s99
	v_xad_u32 v211, v207, 64, s99
	s_waitcnt lgkmcnt(1)
	v_mfma_f32_32x32x16_bf16 v[112:127], v[176:179], v[184:187], v[112:127]
	global_load_dwordx4 v[144:147], v200, s[8:9]
	ds_read_b128 v[160:163], v209
	v_mfma_f32_32x32x16_bf16 v[48:63], v[180:183], v[184:187], v[48:63]
	global_load_dwordx4 v[148:151], v201, s[8:9]
	ds_read_b128 v[164:167], v209 offset:2048
	s_waitcnt lgkmcnt(2)
	v_mfma_f32_32x32x16_bf16 v[96:111], v[176:179], v[188:191], v[96:111]
	global_load_dwordx4 v[152:155], v202, s[8:9]
	ds_read_b128 v[168:171], v211
	v_mfma_f32_32x32x16_bf16 v[32:47], v[180:183], v[188:191], v[32:47]
	global_load_dwordx4 v[156:159], v203, s[8:9]
	ds_read_b128 v[172:175], v211 offset:2048
	s_barrier
	v_xad_u32 v210, v206, 64, s99
	v_xad_u32 v212, v208, 64, s99
	s_waitcnt lgkmcnt(1)
	v_mfma_f32_32x32x16_bf16 v[112:127], v[160:163], v[168:171], v[112:127]
	ds_read_b128 v[176:179], v210
	v_mfma_f32_32x32x16_bf16 v[48:63], v[164:167], v[168:171], v[48:63]
	ds_read_b128 v[180:183], v210 offset:2048
	s_waitcnt lgkmcnt(2)
	v_mfma_f32_32x32x16_bf16 v[96:111], v[160:163], v[172:175], v[96:111]
	ds_read_b128 v[184:187], v212
	s_waitcnt vmcnt(7)
	ds_write_b128 v204, v[128:131]
	v_mfma_f32_32x32x16_bf16 v[32:47], v[164:167], v[172:175], v[32:47]
	ds_read_b128 v[188:191], v212 offset:2048
	s_waitcnt vmcnt(6)
	ds_write_b128 v204, v[132:135] offset:2048
	s_waitcnt lgkmcnt(3)
	v_mfma_f32_32x32x16_bf16 v[112:127], v[176:179], v[184:187], v[112:127]
	s_waitcnt vmcnt(5)
	ds_write_b128 v204, v[136:139] offset:4096
	v_mfma_f32_32x32x16_bf16 v[48:63], v[180:183], v[184:187], v[48:63]
	s_waitcnt vmcnt(4)
	ds_write_b128 v204, v[140:143] offset:6144
	s_waitcnt lgkmcnt(3)
	v_mfma_f32_32x32x16_bf16 v[96:111], v[176:179], v[188:191], v[96:111]
	s_waitcnt vmcnt(3)
	ds_write_b128 v204, v[144:147] offset:8192
	v_mfma_f32_32x32x16_bf16 v[32:47], v[180:183], v[188:191], v[32:47]
	s_waitcnt vmcnt(2)
	ds_write_b128 v204, v[148:151] offset:10240
	s_waitcnt vmcnt(1)
	ds_write_b128 v204, v[152:155] offset:12288
	s_waitcnt vmcnt(0)
	ds_write_b128 v204, v[156:159] offset:14336
	s_add_u32 s6, s6, 0x80
	s_addc_u32 s7, s7, 0
	s_add_u32 s8, s8, 0x80
	s_addc_u32 s9, s9, 0
	s_sub_i32 s98, s98, 0x4000
	s_cmp_lt_i32 s98, 0
	s_cselect_b32 s101, 0xc000, 0
	s_add_i32 s98, s98, s101
	s_sub_i32 s99, s99, 0x4000
	s_cmp_lt_i32 s99, 0
	s_cselect_b32 s101, 0xc000, 0
	s_add_i32 s99, s99, s101
	v_subrev_u32_e32 v213, 0x4000, v204
	v_add_u32_e32 v214, 0x8000, v204
	v_min_u32_e32 v204, v213, v214
	s_add_i32 s100, s100, 1
	s_cmp_lt_u32 s100, 15
	s_waitcnt lgkmcnt(0)
	s_barrier
	s_cbranch_scc1 .Lg7_loop
	v_add_u32_e32 v209, s98, v205
	v_add_u32_e32 v210, s98, v206
	v_add_u32_e32 v211, s98, v207
	v_add_u32_e32 v212, s98, v208
	ds_read_b128 v[160:163], v209
	ds_read_b128 v[164:167], v209 offset:2048
	ds_read_b128 v[168:171], v211
	ds_read_b128 v[172:175], v211 offset:2048
	s_waitcnt lgkmcnt(1)
	v_mfma_f32_32x32x16_bf16 v[112:127], v[160:163], v[168:171], v[112:127]
	ds_read_b128 v[176:179], v210
	v_mfma_f32_32x32x16_bf16 v[48:63], v[164:167], v[168:171], v[48:63]
	ds_read_b128 v[180:183], v210 offset:2048
	s_waitcnt lgkmcnt(2)
	v_mfma_f32_32x32x16_bf16 v[96:111], v[160:163], v[172:175], v[96:111]
	ds_read_b128 v[184:187], v212
	v_mfma_f32_32x32x16_bf16 v[32:47], v[164:167], v[172:175], v[32:47]
	ds_read_b128 v[188:191], v212 offset:2048
	v_xad_u32 v209, v205, 64, s99
	v_xad_u32 v211, v207, 64, s99
	s_waitcnt lgkmcnt(1)
	v_mfma_f32_32x32x16_bf16 v[112:127], v[176:179], v[184:187], v[112:127]
	ds_read_b128 v[160:163], v209
	v_mfma_f32_32x32x16_bf16 v[48:63], v[180:183], v[184:187], v[48:63]
	ds_read_b128 v[164:167], v209 offset:2048
	s_waitcnt lgkmcnt(2)
	v_mfma_f32_32x32x16_bf16 v[96:111], v[176:179], v[188:191], v[96:111]
	ds_read_b128 v[168:171], v211
	v_mfma_f32_32x32x16_bf16 v[32:47], v[180:183], v[188:191], v[32:47]
	ds_read_b128 v[172:175], v211 offset:2048
	v_xad_u32 v210, v206, 64, s99
	v_xad_u32 v212, v208, 64, s99
	s_waitcnt lgkmcnt(1)
	v_mfma_f32_32x32x16_bf16 v[112:127], v[160:163], v[168:171], v[112:127]
	ds_read_b128 v[176:179], v210
	v_mfma_f32_32x32x16_bf16 v[48:63], v[164:167], v[168:171], v[48:63]
	ds_read_b128 v[180:183], v210 offset:2048
	s_waitcnt lgkmcnt(2)
	v_mfma_f32_32x32x16_bf16 v[96:111], v[160:163], v[172:175], v[96:111]
	ds_read_b128 v[184:187], v212
	v_mfma_f32_32x32x16_bf16 v[32:47], v[164:167], v[172:175], v[32:47]
	ds_read_b128 v[188:191], v212 offset:2048
	s_waitcnt lgkmcnt(1)
	v_mfma_f32_32x32x16_bf16 v[112:127], v[176:179], v[184:187], v[112:127]
	v_mfma_f32_32x32x16_bf16 v[48:63], v[180:183], v[184:187], v[48:63]
	s_waitcnt lgkmcnt(0)
	v_mfma_f32_32x32x16_bf16 v[96:111], v[176:179], v[188:191], v[96:111]
	v_mfma_f32_32x32x16_bf16 v[32:47], v[180:183], v[188:191], v[32:47]
	s_setprio 0
	s_nop 7
	s_nop 7
	s_lshl_b32 s1, s38, 1
	s_and_b32 s1, s1, 0xffffff00
	v_lshrrev_b32_e32 v128, 1, v192
	s_add_i32 s1, s1, 0
	v_and_b32_e32 v128, 16, v128
	v_add_u32_e32 v128, s1, v128
	v_add_u32_e32 v163, 0x12000, v128
	s_barrier
	ds_read_b128 v[140:143], v163
	ds_read_b128 v[136:139], v163 offset:32
	ds_read_b128 v[132:135], v163 offset:64
	ds_read_b128 v[128:131], v163 offset:96
	v_mov_b32_e32 v208, v197
	s_waitcnt lgkmcnt(3)
	v_mul_f32_e32 v112, v112, v140
	v_mul_f32_e32 v112, 0xbfb8aa3b, v112
	v_exp_f32_e32 v112, v112
	s_nop 0
	v_add_f32_e32 v112, 1.0, v112
	v_rcp_f32_e32 v112, v112
	s_nop 0
	v_mul_f32_e32 v159, v80, v112
	v_mul_f32_e32 v80, v113, v141
	v_mul_f32_e32 v80, 0xbfb8aa3b, v80
	v_exp_f32_e32 v80, v80
	s_nop 0
	v_add_f32_e32 v80, 1.0, v80
	v_rcp_f32_e32 v80, v80
	s_nop 0
	v_mul_f32_e32 v161, v81, v80
	v_mul_f32_e32 v80, v114, v142
	v_mul_f32_e32 v80, 0xbfb8aa3b, v80
	v_exp_f32_e32 v80, v80
	s_nop 0
	v_add_f32_e32 v80, 1.0, v80
	v_rcp_f32_e32 v80, v80
	s_nop 0
	v_mul_f32_e32 v162, v82, v80
	v_mul_f32_e32 v80, v115, v143
	v_mul_f32_e32 v80, 0xbfb8aa3b, v80
	v_exp_f32_e32 v80, v80
	s_nop 0
	v_add_f32_e32 v80, 1.0, v80
	v_rcp_f32_e32 v80, v80
	s_nop 0
	v_mul_f32_e32 v160, v83, v80
	s_waitcnt lgkmcnt(2)
	v_mul_f32_e32 v80, v116, v136
	v_mul_f32_e32 v80, 0xbfb8aa3b, v80
	v_exp_f32_e32 v80, v80
	s_nop 0
	v_add_f32_e32 v80, 1.0, v80
	v_rcp_f32_e32 v80, v80
	s_nop 0
	v_mul_f32_e32 v158, v84, v80
	v_mul_f32_e32 v80, v117, v137
	v_mul_f32_e32 v80, 0xbfb8aa3b, v80
	v_exp_f32_e32 v80, v80
	s_nop 0
	v_add_f32_e32 v80, 1.0, v80
	v_rcp_f32_e32 v80, v80
	s_nop 0
	v_mul_f32_e32 v157, v85, v80
	v_mul_f32_e32 v80, v118, v138
	v_mul_f32_e32 v80, 0xbfb8aa3b, v80
	v_exp_f32_e32 v80, v80
	s_nop 0
	v_add_f32_e32 v80, 1.0, v80
	v_rcp_f32_e32 v80, v80
	s_nop 0
	v_mul_f32_e32 v156, v86, v80
	v_mul_f32_e32 v80, v119, v139
	v_mul_f32_e32 v80, 0xbfb8aa3b, v80
	v_exp_f32_e32 v80, v80
	s_nop 0
	v_add_f32_e32 v80, 1.0, v80
	v_rcp_f32_e32 v80, v80
	s_nop 0
	v_mul_f32_e32 v155, v87, v80
	s_waitcnt lgkmcnt(1)
	v_mul_f32_e32 v80, v120, v132
	v_mul_f32_e32 v80, 0xbfb8aa3b, v80
	v_exp_f32_e32 v80, v80
	s_nop 0
	v_add_f32_e32 v80, 1.0, v80
	v_rcp_f32_e32 v80, v80
	s_nop 0
	v_mul_f32_e32 v154, v88, v80
	v_mul_f32_e32 v80, v121, v133
	v_mul_f32_e32 v80, 0xbfb8aa3b, v80
	v_exp_f32_e32 v80, v80
	s_nop 0
	v_add_f32_e32 v80, 1.0, v80
	v_rcp_f32_e32 v80, v80
	s_nop 0
	v_mul_f32_e32 v153, v89, v80
	v_mul_f32_e32 v80, v122, v134
	v_mul_f32_e32 v80, 0xbfb8aa3b, v80
	v_exp_f32_e32 v80, v80
	s_nop 0
	v_add_f32_e32 v80, 1.0, v80
	v_rcp_f32_e32 v80, v80
	s_nop 0
	v_mul_f32_e32 v152, v90, v80
	v_mul_f32_e32 v80, v123, v135
	v_mul_f32_e32 v80, 0xbfb8aa3b, v80
	v_exp_f32_e32 v80, v80
	s_nop 0
	v_add_f32_e32 v80, 1.0, v80
	v_rcp_f32_e32 v80, v80
	s_nop 0
	v_mul_f32_e32 v151, v91, v80
	s_waitcnt lgkmcnt(0)
	v_mul_f32_e32 v80, v124, v128
	v_mul_f32_e32 v80, 0xbfb8aa3b, v80
	v_exp_f32_e32 v80, v80
	s_nop 0
	v_add_f32_e32 v80, 1.0, v80
	v_rcp_f32_e32 v80, v80
	s_nop 0
	v_mul_f32_e32 v150, v92, v80
	v_mul_f32_e32 v80, v125, v129
	v_mul_f32_e32 v80, 0xbfb8aa3b, v80
	v_exp_f32_e32 v80, v80
	s_nop 0
	v_add_f32_e32 v80, 1.0, v80
	v_rcp_f32_e32 v80, v80
	s_nop 0
	v_mul_f32_e32 v149, v93, v80
	v_mul_f32_e32 v80, v126, v130
	v_mul_f32_e32 v80, 0xbfb8aa3b, v80
	v_exp_f32_e32 v80, v80
	s_nop 0
	v_add_f32_e32 v80, 1.0, v80
	v_rcp_f32_e32 v80, v80
	s_nop 0
	v_mul_f32_e32 v148, v94, v80
	v_mul_f32_e32 v80, v127, v131
	v_mul_f32_e32 v80, 0xbfb8aa3b, v80
	v_exp_f32_e32 v80, v80
	s_nop 0
	v_add_f32_e32 v80, 1.0, v80
	v_rcp_f32_e32 v80, v80
	s_nop 0
	v_mul_f32_e32 v147, v95, v80
	v_mul_f32_e32 v80, v96, v140
	v_mul_f32_e32 v80, 0xbfb8aa3b, v80
	v_exp_f32_e32 v80, v80
	s_nop 0
	v_add_f32_e32 v80, 1.0, v80
	v_rcp_f32_e32 v80, v80
	s_nop 0
	v_mul_f32_e32 v144, v64, v80
	v_mul_f32_e32 v64, v97, v141
	v_mul_f32_e32 v64, 0xbfb8aa3b, v64
	v_exp_f32_e32 v64, v64
	s_nop 0
	v_add_f32_e32 v64, 1.0, v64
	v_rcp_f32_e32 v64, v64
	s_nop 0
	v_mul_f32_e32 v146, v65, v64
	v_mul_f32_e32 v64, v98, v142
	v_mul_f32_e32 v64, 0xbfb8aa3b, v64
	v_exp_f32_e32 v64, v64
	v_mul_f32_e32 v169, v146, v146
	v_fmac_f32_e32 v169, v161, v161
	v_add_f32_e32 v64, 1.0, v64
	v_rcp_f32_e32 v64, v64
	s_nop 0
	v_mul_f32_e32 v145, v66, v64
	v_mul_f32_e32 v64, v99, v143
	v_mul_f32_e32 v64, 0xbfb8aa3b, v64
	v_exp_f32_e32 v64, v64
	s_nop 0
	v_add_f32_e32 v64, 1.0, v64
	v_rcp_f32_e32 v64, v64
	s_nop 0
	v_mul_f32_e32 v143, v67, v64
	v_mul_f32_e32 v64, v100, v136
	v_mul_f32_e32 v64, 0xbfb8aa3b, v64
	v_exp_f32_e32 v64, v64
	s_nop 0
	v_add_f32_e32 v64, 1.0, v64
	v_rcp_f32_e32 v64, v64
	s_nop 0
	v_mul_f32_e32 v142, v68, v64
	v_mul_f32_e32 v64, v101, v137
	v_mul_f32_e32 v64, 0xbfb8aa3b, v64
	v_exp_f32_e32 v64, v64
	v_mul_f32_e32 v177, v142, v142
	v_fmac_f32_e32 v177, v158, v158
	v_add_f32_e32 v64, 1.0, v64
	v_rcp_f32_e32 v64, v64
	s_nop 0
	v_mul_f32_e32 v141, v69, v64
	v_mul_f32_e32 v64, v102, v138
	v_mul_f32_e32 v64, 0xbfb8aa3b, v64
	v_exp_f32_e32 v64, v64
	v_mul_f32_e32 v179, v141, v141
	v_fmac_f32_e32 v179, v157, v157
	v_add_f32_e32 v64, 1.0, v64
	v_rcp_f32_e32 v64, v64
	s_nop 0
	v_mul_f32_e32 v140, v70, v64
	v_mul_f32_e32 v64, v103, v139
	v_mul_f32_e32 v64, 0xbfb8aa3b, v64
	v_exp_f32_e32 v64, v64
	v_mul_f32_e32 v180, v140, v140
	v_fmac_f32_e32 v180, v156, v156
	v_add_f32_e32 v64, 1.0, v64
	v_rcp_f32_e32 v64, v64
	s_nop 0
	v_mul_f32_e32 v138, v71, v64
	v_mul_f32_e32 v64, v104, v132
	v_mul_f32_e32 v64, 0xbfb8aa3b, v64
	v_exp_f32_e32 v64, v64
	v_mul_f32_e32 v182, v138, v138
	v_fmac_f32_e32 v182, v155, v155
	v_add_f32_e32 v64, 1.0, v64
	v_rcp_f32_e32 v64, v64
	s_nop 0
	v_mul_f32_e32 v137, v72, v64
	v_mul_f32_e32 v64, v105, v133
	v_mul_f32_e32 v64, 0xbfb8aa3b, v64
	v_exp_f32_e32 v64, v64
	v_mul_f32_e32 v184, v137, v137
	v_fmac_f32_e32 v184, v154, v154
	v_add_f32_e32 v64, 1.0, v64
	v_rcp_f32_e32 v64, v64
	s_nop 0
	v_mul_f32_e32 v136, v73, v64
	v_mul_f32_e32 v64, v106, v134
	v_mul_f32_e32 v64, 0xbfb8aa3b, v64
	v_exp_f32_e32 v64, v64
	s_nop 0
	v_add_f32_e32 v64, 1.0, v64
	v_rcp_f32_e32 v64, v64
	s_nop 0
	v_mul_f32_e32 v134, v74, v64
	v_mul_f32_e32 v64, v107, v135
	v_mul_f32_e32 v64, 0xbfb8aa3b, v64
	v_exp_f32_e32 v64, v64
	s_nop 0
	v_add_f32_e32 v64, 1.0, v64
	v_rcp_f32_e32 v64, v64
	s_nop 0
	v_mul_f32_e32 v133, v75, v64
	v_mul_f32_e32 v64, v108, v128
	v_mul_f32_e32 v64, 0xbfb8aa3b, v64
	v_exp_f32_e32 v64, v64
	v_mul_f32_e32 v189, v133, v133
	v_fmac_f32_e32 v189, v151, v151
	v_add_f32_e32 v64, 1.0, v64
	v_rcp_f32_e32 v64, v64
	s_nop 0
	v_mul_f32_e32 v132, v76, v64
	v_mul_f32_e32 v64, v109, v129
	v_mul_f32_e32 v64, 0xbfb8aa3b, v64
	v_exp_f32_e32 v64, v64
	v_mul_f32_e32 v196, v132, v132
	v_fmac_f32_e32 v196, v150, v150
	v_add_f32_e32 v64, 1.0, v64
	v_rcp_f32_e32 v64, v64
	s_nop 0
	v_mul_f32_e32 v128, v77, v64
	v_mul_f32_e32 v64, v110, v130
	v_mul_f32_e32 v64, 0xbfb8aa3b, v64
	v_exp_f32_e32 v64, v64
	s_nop 0
	v_add_f32_e32 v64, 1.0, v64
	v_rcp_f32_e32 v64, v64
	s_nop 0
	v_mul_f32_e32 v125, v78, v64
	v_mul_f32_e32 v64, v111, v131
	v_mul_f32_e32 v64, 0xbfb8aa3b, v64
	v_exp_f32_e32 v64, v64
	v_mul_f32_e32 v209, v125, v125
	v_fmac_f32_e32 v209, v148, v148
	v_add_f32_e32 v64, 1.0, v64
	v_rcp_f32_e32 v64, v64
	s_nop 0
	v_mul_f32_e32 v127, v79, v64
	ds_read_b128 v[76:79], v163 offset:128
	ds_read_b128 v[72:75], v163 offset:160
	ds_read_b128 v[68:71], v163 offset:192
	ds_read_b128 v[64:67], v163 offset:224
	s_nop 0
	v_readfirstlane_b32 s1, v208
	s_ashr_i32 s7, s1, 7
	s_bfe_u32 s8, s1, 0x10006
	s_lshl_b32 s1, s68, 1
	v_bfe_u32 v205, v208, 5, 1
	s_and_b32 s6, s1, 14
	s_lshl_b32 s1, s7, 6
	s_add_i32 s9, s1, s0
	v_lshlrev_b32_e32 v84, 2, v205
	v_or_b32_e32 v86, s9, v84
	s_lshl_b32 s9, s93, 1
	s_add_u32 s9, s66, s9
	s_addc_u32 s37, s67, 0
	s_lshl_b32 s36, s8, 7
	v_and_b32_e32 v206, 31, v208
	s_add_u32 s36, s9, s36
	s_addc_u32 s37, s37, 0
	v_lshlrev_b32_e32 v198, 1, v206
	v_ashrrev_i32_e32 v87, 31, v86
	v_lshl_add_u64 v[90:91], s[36:37], 0, v[198:199]
	v_lshlrev_b64 v[88:89], 11, v[86:87]
	v_lshl_add_u64 v[80:81], v[90:91], 0, v[88:89]
	v_add_co_u32_e32 v82, vcc, s96, v80
	global_load_ushort v207, v[80:81], off
	global_load_ushort v204, v[80:81], off offset:2048
	v_addc_co_u32_e32 v83, vcc, 0, v81, vcc
	v_add_co_u32_e32 v92, vcc, s94, v80
	global_load_ushort v203, v[82:83], off
	global_load_ushort v202, v[82:83], off offset:2048
	v_addc_co_u32_e32 v93, vcc, 0, v81, vcc
	v_add_co_u32_e32 v94, vcc, s57, v80
	v_and_b32_e32 v85, 16, v208
	s_nop 0
	v_addc_co_u32_e32 v95, vcc, 0, v81, vcc
	v_add_co_u32_e32 v96, vcc, s35, v80
	global_load_ushort v201, v[94:95], off offset:-4096
	global_load_ushort v200, v[92:93], off offset:2048
	global_load_ushort v195, v[94:95], off
	global_load_ushort v194, v[94:95], off offset:2048
	v_addc_co_u32_e32 v97, vcc, 0, v81, vcc
	v_add_co_u32_e32 v98, vcc, s58, v80
	v_cmp_eq_u32_e64 s[42:43], 0, v85
	s_nop 0
	v_addc_co_u32_e32 v99, vcc, 0, v81, vcc
	v_add_co_u32_e32 v100, vcc, s95, v80
	global_load_ushort v193, v[98:99], off offset:-4096
	global_load_ushort v192, v[96:97], off offset:2048
	global_load_ushort v191, v[98:99], off
	global_load_ushort v190, v[98:99], off offset:2048
	v_addc_co_u32_e32 v101, vcc, 0, v81, vcc
	v_add_co_u32_e32 v102, vcc, s59, v80
	v_and_b32_e32 v85, 8, v208
	s_nop 0
	v_addc_co_u32_e32 v103, vcc, 0, v81, vcc
	global_load_ushort v188, v[102:103], off offset:-4096
	global_load_ushort v185, v[100:101], off offset:2048
	global_load_ushort v183, v[102:103], off
	global_load_ushort v181, v[102:103], off offset:2048
	global_load_ushort v178, v[80:81], off offset:64
	global_load_ushort v176, v[80:81], off offset:2112
	global_load_ushort v174, v[82:83], off offset:64
	global_load_ushort v175, v[82:83], off offset:2112
	global_load_ushort v171, v[92:93], off offset:64
	global_load_ushort v170, v[92:93], off offset:2112
	global_load_ushort v168, v[94:95], off offset:64
	global_load_ushort v167, v[94:95], off offset:2112
	global_load_ushort v166, v[96:97], off offset:64
	global_load_ushort v165, v[96:97], off offset:2112
	global_load_ushort v164, v[98:99], off offset:64
	global_load_ushort v163, v[98:99], off offset:2112
	global_load_ushort v139, v[100:101], off offset:64
	global_load_ushort v135, v[100:101], off offset:2112
	global_load_ushort v131, v[102:103], off offset:64
	global_load_ushort v130, v[102:103], off offset:2112
	v_or_b32_e32 v80, 32, v86
	v_ashrrev_i32_e32 v81, 31, v80
	v_lshlrev_b64 v[82:83], 11, v[80:81]
	v_lshl_add_u64 v[90:91], v[90:91], 0, v[82:83]
	v_add_co_u32_e32 v92, vcc, s96, v90
	global_load_ushort v129, v[90:91], off
	global_load_ushort v126, v[90:91], off offset:2048
	v_addc_co_u32_e32 v93, vcc, 0, v91, vcc
	v_add_co_u32_e32 v94, vcc, s94, v90
	global_load_ushort v124, v[92:93], off
	global_load_ushort v123, v[92:93], off offset:2048
	v_addc_co_u32_e32 v95, vcc, 0, v91, vcc
	v_add_co_u32_e32 v96, vcc, s57, v90
	v_cmp_eq_u32_e64 s[38:39], 0, v85
	s_nop 0
	v_addc_co_u32_e32 v97, vcc, 0, v91, vcc
	v_add_co_u32_e32 v98, vcc, s35, v90
	global_load_ushort v122, v[96:97], off offset:-4096
	global_load_ushort v121, v[94:95], off offset:2048
	global_load_ushort v120, v[96:97], off
	global_load_ushort v119, v[96:97], off offset:2048
	v_addc_co_u32_e32 v99, vcc, 0, v91, vcc
	v_add_co_u32_e32 v172, vcc, s58, v90
	v_xor_b32_e32 v85, 8, v219
	s_nop 0
	v_addc_co_u32_e32 v173, vcc, 0, v91, vcc
	v_add_co_u32_e32 v186, vcc, s95, v90
	global_load_ushort v118, v[172:173], off offset:-4096
	global_load_ushort v117, v[98:99], off offset:2048
	global_load_ushort v116, v[172:173], off
	global_load_ushort v115, v[172:173], off offset:2048
	v_addc_co_u32_e32 v187, vcc, 0, v91, vcc
	v_add_co_u32_e32 v210, vcc, s59, v90
	v_mul_f32_e32 v198, v128, v128
	s_nop 0
	v_addc_co_u32_e32 v211, vcc, 0, v91, vcc
	global_load_ushort v114, v[210:211], off offset:-4096
	global_load_ushort v113, v[186:187], off offset:2048
	global_load_ushort v112, v[210:211], off
	global_load_ushort v111, v[210:211], off offset:2048
	global_load_ushort v110, v[90:91], off offset:64
	global_load_ushort v108, v[90:91], off offset:2112
	global_load_ushort v109, v[92:93], off offset:64
	global_load_ushort v107, v[92:93], off offset:2112
	global_load_ushort v106, v[94:95], off offset:64
	global_load_ushort v105, v[94:95], off offset:2112
	global_load_ushort v104, v[96:97], off offset:64
	global_load_ushort v103, v[96:97], off offset:2112
	global_load_ushort v102, v[98:99], off offset:64
	global_load_ushort v101, v[98:99], off offset:2112
	global_load_ushort v100, v[172:173], off offset:64
	s_nop 0
	global_load_ushort v99, v[172:173], off offset:2112
	global_load_ushort v98, v[186:187], off offset:64
	global_load_ushort v97, v[186:187], off offset:2112
	global_load_ushort v95, v[210:211], off offset:64
	global_load_ushort v96, v[210:211], off offset:2112
	v_and_b32_e32 v92, 64, v219
	v_xor_b32_e32 v91, 16, v219
	v_add_u32_e32 v92, 64, v92
	v_cmp_lt_i32_e32 vcc, v91, v92
	v_and_b32_e32 v90, 4, v208
	v_cmp_eq_u32_e64 s[36:37], 0, v90
	v_cndmask_b32_e32 v91, v219, v91, vcc
	v_cmp_lt_i32_e32 vcc, v85, v92
	v_lshlrev_b32_e32 v94, 2, v91
	v_mul_f32_e32 v186, v136, v136
	v_cndmask_b32_e32 v85, v219, v85, vcc
	v_lshlrev_b32_e32 v93, 2, v85
	v_xor_b32_e32 v85, 4, v219
	v_cmp_lt_i32_e32 vcc, v85, v92
	v_fmac_f32_e32 v186, v153, v153
	v_mul_f32_e32 v172, v145, v145
	v_cndmask_b32_e32 v85, v219, v85, vcc
	v_lshlrev_b32_e32 v90, 2, v85
	v_and_b32_e32 v85, 2, v208
	v_cmp_eq_u32_e64 s[40:41], 0, v85
	v_xor_b32_e32 v85, 2, v219
	v_cmp_lt_i32_e32 vcc, v85, v92
	v_mul_f32_e32 v187, v134, v134
	v_fmac_f32_e32 v172, v162, v162
	v_cndmask_b32_e32 v85, v219, v85, vcc
	v_lshlrev_b32_e32 v91, 2, v85
	v_xor_b32_e32 v85, 1, v219
	v_cmp_lt_i32_e32 vcc, v85, v92
	v_fmac_f32_e32 v187, v152, v152
	v_mul_f32_e32 v173, v143, v143
	v_cndmask_b32_e32 v85, v219, v85, vcc
	v_lshlrev_b32_e32 v92, 2, v85
	v_and_b32_e32 v85, 1, v208
	v_cmp_eq_u32_e64 s[44:45], 0, v85
	v_bfe_u32 v85, v208, 1, 2
	v_and_or_b32 v85, v208, 24, v85
	v_or3_b32 v84, v85, s0, v84
	v_mul_f32_e32 v85, v144, v144
	v_fmac_f32_e32 v85, v159, v159
	v_cndmask_b32_e64 v211, v184, v85, s[42:43]
	v_cndmask_b32_e64 v85, v85, v184, s[42:43]
	v_cndmask_b32_e64 v184, v186, v169, s[42:43]
	v_cndmask_b32_e64 v169, v169, v186, s[42:43]
	ds_bpermute_b32 v169, v94, v169
	v_fmac_f32_e32 v173, v160, v160
	v_fmac_f32_e32 v198, v149, v149
	v_mul_f32_e32 v210, v127, v127
	v_fmac_f32_e32 v210, v147, v147
	s_waitcnt lgkmcnt(0)
	v_add_f32_e32 v169, v184, v169
	v_cndmask_b32_e64 v184, v187, v172, s[42:43]
	v_cndmask_b32_e64 v172, v172, v187, s[42:43]
	ds_bpermute_b32 v172, v94, v172
	ds_bpermute_b32 v85, v94, v85
	s_or_b32 s6, s8, s6
	v_add_u32_e32 v84, s1, v84
	s_lshl_b32 s1, s6, 3
	s_waitcnt lgkmcnt(1)
	v_add_f32_e32 v172, v184, v172
	v_cndmask_b32_e64 v184, v189, v173, s[42:43]
	v_cndmask_b32_e64 v173, v173, v189, s[42:43]
	ds_bpermute_b32 v173, v94, v173
	s_waitcnt lgkmcnt(1)
	v_add_f32_e32 v85, v211, v85
	s_add_u32 s46, s30, s1
	s_addc_u32 s47, s31, 0
	s_waitcnt lgkmcnt(0)
	v_add_f32_e32 v173, v184, v173
	v_cndmask_b32_e64 v184, v196, v177, s[42:43]
	v_cndmask_b32_e64 v177, v177, v196, s[42:43]
	ds_bpermute_b32 v177, v94, v177
	s_waitcnt lgkmcnt(0)
	v_add_f32_e32 v177, v184, v177
	v_cndmask_b32_e64 v184, v198, v179, s[42:43]
	v_cndmask_b32_e64 v179, v179, v198, s[42:43]
	ds_bpermute_b32 v179, v94, v179
	s_waitcnt lgkmcnt(0)
	v_add_f32_e32 v179, v184, v179
	v_cndmask_b32_e64 v184, v209, v180, s[42:43]
	v_cndmask_b32_e64 v180, v180, v209, s[42:43]
	ds_bpermute_b32 v180, v94, v180
	s_waitcnt lgkmcnt(0)
	v_add_f32_e32 v180, v184, v180
	v_cndmask_b32_e64 v184, v210, v182, s[42:43]
	v_cndmask_b32_e64 v182, v182, v210, s[42:43]
	ds_bpermute_b32 v182, v94, v182
	s_waitcnt lgkmcnt(0)
	v_add_f32_e32 v182, v184, v182
	v_cndmask_b32_e64 v184, v177, v85, s[38:39]
	v_cndmask_b32_e64 v85, v85, v177, s[38:39]
	v_cndmask_b32_e64 v177, v179, v169, s[38:39]
	v_cndmask_b32_e64 v169, v169, v179, s[38:39]
	ds_bpermute_b32 v169, v93, v169
	ds_bpermute_b32 v85, v93, v85
	s_waitcnt lgkmcnt(1)
	v_add_f32_e32 v169, v177, v169
	v_cndmask_b32_e64 v177, v180, v172, s[38:39]
	v_cndmask_b32_e64 v172, v172, v180, s[38:39]
	ds_bpermute_b32 v172, v93, v172
	s_waitcnt lgkmcnt(1)
	v_add_f32_e32 v85, v184, v85
	s_waitcnt lgkmcnt(0)
	v_add_f32_e32 v172, v177, v172
	v_cndmask_b32_e64 v177, v182, v173, s[38:39]
	v_cndmask_b32_e64 v173, v173, v182, s[38:39]
	ds_bpermute_b32 v173, v93, v173
	s_waitcnt lgkmcnt(0)
	v_add_f32_e32 v173, v177, v173
	v_cndmask_b32_e64 v177, v172, v85, s[36:37]
	v_cndmask_b32_e64 v85, v85, v172, s[36:37]
	v_cndmask_b32_e64 v172, v173, v169, s[36:37]
	v_cndmask_b32_e64 v169, v169, v173, s[36:37]
	ds_bpermute_b32 v85, v90, v85
	ds_bpermute_b32 v169, v90, v169
	s_waitcnt lgkmcnt(1)
	v_add_f32_e32 v85, v177, v85
	s_waitcnt lgkmcnt(0)
	v_add_f32_e32 v169, v172, v169
	v_cndmask_b32_e64 v172, v169, v85, s[40:41]
	v_cndmask_b32_e64 v85, v85, v169, s[40:41]
	ds_bpermute_b32 v85, v91, v85
	s_waitcnt lgkmcnt(0)
	v_add_f32_e32 v169, v172, v85
	ds_bpermute_b32 v172, v92, v169
	v_ashrrev_i32_e32 v85, 31, v84
	s_and_saveexec_b64 s[48:49], s[44:45]
	s_cbranch_execz .LBB0_632
	v_lshlrev_b64 v[186:187], 7, v[84:85]
	s_waitcnt lgkmcnt(0)
	v_add_f32_e32 v172, v169, v172
	v_lshl_add_u64 v[186:187], s[46:47], 0, v[186:187]
	v_mov_b32_e32 v173, s92
	global_store_dwordx2 v[186:187], v[172:173], off sc1

.LBB0_640:
	s_or_b64 exec, exec, s[46:47]
	s_lshl_b32 s0, s8, 6
	v_or_b32_e32 v0, s93, v206
	v_or_b32_e32 v4, s0, v0
	v_lshlrev_b32_e32 v198, 2, v4
	s_waitcnt lgkmcnt(0)
	s_barrier
	global_load_dword v24, v198, s[50:51]
	global_load_dword v244, v198, s[50:51] offset:128
	s_lshl_b32 s0, s7, 8
	s_add_i32 s0, s0, 0
	v_lshlrev_b32_e32 v5, 4, v205
	s_add_i32 s0, s0, 0x12000
	v_add_u32_e32 v26, s0, v5
	v_lshlrev_b64 v[0:1], 12, v[86:87]
	ds_read_b128 v[12:15], v26 offset:512
	v_lshl_add_u64 v[2:3], s[66:67], 0, v[88:89]
	v_mov_b32_e32 v19, v199
	v_cndmask_b32_e64 v6, 0, 1, s[26:27]
	v_lshl_add_u64 v[0:1], s[28:29], 0, v[0:1]
	v_lshlrev_b32_e32 v18, 1, v4
	v_cmp_ne_u32_e64 s[46:47], 1, v6
	v_lshl_add_u64 v[22:23], v[0:1], 0, v[198:199]
	v_lshl_add_u64 v[20:21], v[2:3], 0, v[18:19]
	ds_read_b128 v[8:11], v26 offset:544
	ds_read_b128 v[4:7], v26 offset:576
	ds_read_b128 v[0:3], v26 offset:608
	v_lshlrev_b32_e32 v25, 16, v207
	s_waitcnt lgkmcnt(3)
	v_mul_f32_e32 v19, v12, v159
	s_andn2_b64 vcc, exec, s[26:27]
	s_waitcnt vmcnt(0)
	v_fmac_f32_e32 v25, v24, v19
	v_cvt_pk_bf16_f32 v19, v25, s0
	global_store_short v[20:21], v19, off
	s_cbranch_vccnz .LBB0_642
	global_store_dword v[22:23], v25, off

.LBB0_672:
	v_lshl_add_u64 v[64:65], s[50:51], 0, v[198:199]
	v_lshlrev_b32_e32 v64, 16, v178
	v_mul_f32_e32 v12, v12, v144
	v_lshl_add_u64 v[22:23], v[22:23], 0, s[76:77]
	s_and_b64 vcc, exec, s[46:47]
	v_fmac_f32_e32 v64, v244, v12
	v_cvt_pk_bf16_f32 v62, v64, s0
	global_store_short v[20:21], v62, off offset:64
	s_cbranch_vccnz .LBB0_674
	global_store_dword v[22:23], v64, off
.LBB0_674:
	v_lshlrev_b32_e32 v12, 16, v176
	v_mul_f32_e32 v13, v13, v146
	v_fmac_f32_e32 v12, v244, v13
	v_cvt_pk_bf16_f32 v64, v12, s0
	s_and_b64 vcc, exec, s[46:47]
	global_store_short v[20:21], v64, off offset:2112
	s_cbranch_vccnz .LBB0_676
	v_add_co_u32_e32 v66, vcc, 0x1000, v22
	s_nop 1
	v_addc_co_u32_e32 v67, vcc, 0, v23, vcc
	global_store_dword v[66:67], v12, off
.LBB0_676:
	v_lshl_add_u64 v[12:13], v[20:21], 0, 64
	v_lshlrev_b32_e32 v20, 16, v174
	v_mul_f32_e32 v14, v14, v145
	v_add_co_u32_e32 v66, vcc, 0x1000, v12
	v_fmac_f32_e32 v20, v244, v14
	s_nop 0
	v_addc_co_u32_e32 v67, vcc, 0, v13, vcc
	v_cvt_pk_bf16_f32 v14, v20, s0
	s_and_b64 vcc, exec, s[46:47]
	global_store_short v[66:67], v14, off
	s_cbranch_vccnz .LBB0_678
	v_add_co_u32_e32 v66, vcc, 0x2000, v22
	s_nop 1
	v_addc_co_u32_e32 v67, vcc, 0, v23, vcc
	global_store_dword v[66:67], v20, off
.LBB0_678:
	v_lshlrev_b32_e32 v20, 16, v175
	v_mul_f32_e32 v15, v15, v143
	v_add_co_u32_e32 v66, vcc, 0x1000, v12
	v_fmac_f32_e32 v20, v244, v15
	s_nop 0
	v_addc_co_u32_e32 v67, vcc, 0, v13, vcc
	v_cvt_pk_bf16_f32 v15, v20, s0
	s_and_b64 vcc, exec, s[46:47]
	global_store_short v[66:67], v15, off offset:2048
	s_cbranch_vccnz .LBB0_680
	v_add_co_u32_e32 v66, vcc, 0x3000, v22
	s_nop 1
	v_addc_co_u32_e32 v67, vcc, 0, v23, vcc
	global_store_dword v[66:67], v20, off
.LBB0_680:
	v_lshlrev_b32_e32 v20, 16, v171
	v_mul_f32_e32 v8, v8, v142
	v_add_co_u32_e32 v66, vcc, 0x4000, v12
	v_fmac_f32_e32 v20, v244, v8
	s_nop 0
	v_addc_co_u32_e32 v67, vcc, 0, v13, vcc
	v_cvt_pk_bf16_f32 v8, v20, s0
	s_and_b64 vcc, exec, s[46:47]
	global_store_short v[66:67], v8, off
	s_cbranch_vccnz .LBB0_682
	v_add_co_u32_e32 v66, vcc, 0x8000, v22
	s_nop 1
	v_addc_co_u32_e32 v67, vcc, 0, v23, vcc
	global_store_dword v[66:67], v20, off
.LBB0_682:
	v_lshlrev_b32_e32 v20, 16, v170
	v_mul_f32_e32 v9, v9, v141
	v_add_co_u32_e32 v66, vcc, 0x4000, v12
	v_fmac_f32_e32 v20, v244, v9
	s_nop 0
	v_addc_co_u32_e32 v67, vcc, 0, v13, vcc
	v_cvt_pk_bf16_f32 v9, v20, s0
	s_and_b64 vcc, exec, s[46:47]
	global_store_short v[66:67], v9, off offset:2048
	s_cbranch_vccnz .LBB0_684
	v_add_co_u32_e32 v66, vcc, 0x9000, v22
	s_nop 1
	v_addc_co_u32_e32 v67, vcc, 0, v23, vcc
	global_store_dword v[66:67], v20, off
.LBB0_684:
	v_lshlrev_b32_e32 v20, 16, v168
	v_mul_f32_e32 v10, v10, v140
	v_add_co_u32_e32 v66, vcc, 0x5000, v12
	v_fmac_f32_e32 v20, v244, v10
	s_nop 0
	v_addc_co_u32_e32 v67, vcc, 0, v13, vcc
	v_cvt_pk_bf16_f32 v10, v20, s0
	s_and_b64 vcc, exec, s[46:47]
	global_store_short v[66:67], v10, off
	s_cbranch_vccnz .LBB0_686
	v_add_co_u32_e32 v66, vcc, 0xa000, v22
	s_nop 1
	v_addc_co_u32_e32 v67, vcc, 0, v23, vcc
	global_store_dword v[66:67], v20, off
.LBB0_686:
	v_lshlrev_b32_e32 v20, 16, v167
	v_mul_f32_e32 v11, v11, v138
	v_add_co_u32_e32 v66, vcc, 0x5000, v12
	v_fmac_f32_e32 v20, v244, v11
	s_nop 0
	v_addc_co_u32_e32 v67, vcc, 0, v13, vcc
	v_cvt_pk_bf16_f32 v11, v20, s0
	s_and_b64 vcc, exec, s[46:47]
	global_store_short v[66:67], v11, off offset:2048
	s_cbranch_vccnz .LBB0_688
	v_add_co_u32_e32 v66, vcc, 0xb000, v22
	s_nop 1
	v_addc_co_u32_e32 v67, vcc, 0, v23, vcc
	global_store_dword v[66:67], v20, off
.LBB0_688:
	v_lshlrev_b32_e32 v20, 16, v166
	v_mul_f32_e32 v4, v4, v137
	v_add_co_u32_e32 v66, vcc, 0x8000, v12
	v_fmac_f32_e32 v20, v244, v4
	s_nop 0
	v_addc_co_u32_e32 v67, vcc, 0, v13, vcc
	v_cvt_pk_bf16_f32 v4, v20, s0
	s_and_b64 vcc, exec, s[46:47]
	global_store_short v[66:67], v4, off
	s_cbranch_vccnz .LBB0_690
	v_add_co_u32_e32 v66, vcc, 0x10000, v22
	s_nop 1
	v_addc_co_u32_e32 v67, vcc, 0, v23, vcc
	global_store_dword v[66:67], v20, off
.LBB0_690:
	v_lshlrev_b32_e32 v20, 16, v165
	v_mul_f32_e32 v5, v5, v136
	v_add_co_u32_e32 v66, vcc, 0x8000, v12
	v_fmac_f32_e32 v20, v244, v5
	s_nop 0
	v_addc_co_u32_e32 v67, vcc, 0, v13, vcc
	v_cvt_pk_bf16_f32 v5, v20, s0
	s_and_b64 vcc, exec, s[46:47]
	global_store_short v[66:67], v5, off offset:2048
	s_cbranch_vccnz .LBB0_692
	v_add_co_u32_e32 v66, vcc, 0x11000, v22
	s_nop 1
	v_addc_co_u32_e32 v67, vcc, 0, v23, vcc
	global_store_dword v[66:67], v20, off
.LBB0_692:
	v_lshlrev_b32_e32 v20, 16, v164
	v_mul_f32_e32 v6, v6, v134
	v_add_co_u32_e32 v66, vcc, 0x9000, v12
	v_fmac_f32_e32 v20, v244, v6
	s_nop 0
	v_addc_co_u32_e32 v67, vcc, 0, v13, vcc
	v_cvt_pk_bf16_f32 v6, v20, s0
	s_and_b64 vcc, exec, s[46:47]
	global_store_short v[66:67], v6, off
	s_cbranch_vccnz .LBB0_694
	v_add_co_u32_e32 v66, vcc, 0x12000, v22
	s_nop 1
	v_addc_co_u32_e32 v67, vcc, 0, v23, vcc
	global_store_dword v[66:67], v20, off
.LBB0_694:
	v_lshlrev_b32_e32 v20, 16, v163
	v_mul_f32_e32 v7, v7, v133
	v_add_co_u32_e32 v66, vcc, 0x9000, v12
	v_fmac_f32_e32 v20, v244, v7
	s_nop 0
	v_addc_co_u32_e32 v67, vcc, 0, v13, vcc
	v_cvt_pk_bf16_f32 v7, v20, s0
	s_and_b64 vcc, exec, s[46:47]
	global_store_short v[66:67], v7, off offset:2048
	s_cbranch_vccnz .LBB0_696
	v_add_co_u32_e32 v66, vcc, 0x13000, v22
	s_nop 1
	v_addc_co_u32_e32 v67, vcc, 0, v23, vcc
	global_store_dword v[66:67], v20, off
.LBB0_696:
	v_lshlrev_b32_e32 v20, 16, v139
	v_mul_f32_e32 v0, v0, v132
	v_add_co_u32_e32 v66, vcc, 0xc000, v12
	v_fmac_f32_e32 v20, v244, v0
	s_nop 0
	v_addc_co_u32_e32 v67, vcc, 0, v13, vcc
	v_cvt_pk_bf16_f32 v0, v20, s0
	s_and_b64 vcc, exec, s[46:47]
	global_store_short v[66:67], v0, off
	s_cbranch_vccnz .LBB0_698
	v_add_co_u32_e32 v66, vcc, 0x18000, v22
	s_nop 1
	v_addc_co_u32_e32 v67, vcc, 0, v23, vcc
	global_store_dword v[66:67], v20, off
.LBB0_698:
	v_lshlrev_b32_e32 v20, 16, v135
	v_mul_f32_e32 v1, v1, v128
	v_add_co_u32_e32 v66, vcc, 0xc000, v12
	v_fmac_f32_e32 v20, v244, v1
	s_nop 0
	v_addc_co_u32_e32 v67, vcc, 0, v13, vcc
	v_cvt_pk_bf16_f32 v1, v20, s0
	s_and_b64 vcc, exec, s[46:47]
	global_store_short v[66:67], v1, off offset:2048
	s_cbranch_vccnz .LBB0_700
	v_add_co_u32_e32 v66, vcc, 0x19000, v22
	s_nop 1
	v_addc_co_u32_e32 v67, vcc, 0, v23, vcc
	global_store_dword v[66:67], v20, off
.LBB0_700:
	v_lshlrev_b32_e32 v20, 16, v131
	v_mul_f32_e32 v2, v2, v125
	v_add_co_u32_e32 v66, vcc, 0xd000, v12
	v_fmac_f32_e32 v20, v244, v2
	s_nop 0
	v_addc_co_u32_e32 v67, vcc, 0, v13, vcc
	v_cvt_pk_bf16_f32 v2, v20, s0
	s_and_b64 vcc, exec, s[46:47]
	global_store_short v[66:67], v2, off
	s_cbranch_vccnz .LBB0_702
	v_add_co_u32_e32 v66, vcc, 0x1a000, v22
	s_nop 1
	v_addc_co_u32_e32 v67, vcc, 0, v23, vcc
	global_store_dword v[66:67], v20, off
.LBB0_702:
	v_lshlrev_b32_e32 v20, 16, v130
	v_mul_f32_e32 v3, v3, v127
	v_add_co_u32_e32 v12, vcc, 0xd000, v12
	v_fmac_f32_e32 v20, v244, v3
	s_nop 0
	v_addc_co_u32_e32 v13, vcc, 0, v13, vcc
	v_cvt_pk_bf16_f32 v3, v20, s0
	s_and_b64 vcc, exec, s[46:47]
	global_store_short v[12:13], v3, off offset:2048
	s_cbranch_vccnz .LBB0_704
	v_add_co_u32_e32 v12, vcc, 0x1b000, v22
	s_nop 1
	v_addc_co_u32_e32 v13, vcc, 0, v23, vcc
	global_store_dword v[12:13], v20, off

.LBB0_738:
	v_lshlrev_b32_e32 v56, 16, v110
	v_mul_f32_e32 v12, v12, v55
	v_fmac_f32_e32 v56, v244, v12
	v_lshl_add_u64 v[20:21], v[20:21], 0, s[76:77]
	v_cvt_pk_bf16_f32 v46, v56, s0
	s_and_b64 vcc, exec, s[46:47]
	global_store_short v[18:19], v46, off offset:64
	s_cbranch_vccnz .LBB0_740
	global_store_dword v[20:21], v56, off
.LBB0_740:
	v_lshlrev_b32_e32 v12, 16, v108
	v_mul_f32_e32 v13, v13, v54
	v_fmac_f32_e32 v12, v244, v13
	v_cvt_pk_bf16_f32 v54, v12, s0
	s_and_b64 vcc, exec, s[46:47]
	global_store_short v[18:19], v54, off offset:2112
	s_cbranch_vccnz .LBB0_742
	v_add_co_u32_e32 v56, vcc, 0x1000, v20
	s_nop 1
	v_addc_co_u32_e32 v57, vcc, 0, v21, vcc
	global_store_dword v[56:57], v12, off
.LBB0_742:
	v_lshl_add_u64 v[12:13], v[18:19], 0, 64
	v_lshlrev_b32_e32 v18, 16, v109
	v_mul_f32_e32 v14, v14, v53
	v_add_co_u32_e32 v56, vcc, 0x1000, v12
	v_fmac_f32_e32 v18, v244, v14
	s_nop 0
	v_addc_co_u32_e32 v57, vcc, 0, v13, vcc
	v_cvt_pk_bf16_f32 v14, v18, s0
	s_and_b64 vcc, exec, s[46:47]
	global_store_short v[56:57], v14, off
	s_cbranch_vccnz .LBB0_744
	v_add_co_u32_e32 v56, vcc, 0x2000, v20
	s_nop 1
	v_addc_co_u32_e32 v57, vcc, 0, v21, vcc
	global_store_dword v[56:57], v18, off
.LBB0_744:
	v_lshlrev_b32_e32 v18, 16, v107
	v_mul_f32_e32 v15, v15, v52
	v_add_co_u32_e32 v52, vcc, 0x1000, v12
	v_fmac_f32_e32 v18, v244, v15
	s_nop 0
	v_addc_co_u32_e32 v53, vcc, 0, v13, vcc
	v_cvt_pk_bf16_f32 v15, v18, s0
	s_and_b64 vcc, exec, s[46:47]
	global_store_short v[52:53], v15, off offset:2048
	s_cbranch_vccnz .LBB0_746
	v_add_co_u32_e32 v52, vcc, 0x3000, v20
	s_nop 1
	v_addc_co_u32_e32 v53, vcc, 0, v21, vcc
	global_store_dword v[52:53], v18, off
.LBB0_746:
	v_lshlrev_b32_e32 v18, 16, v106
	v_mul_f32_e32 v8, v8, v51
	v_add_co_u32_e32 v52, vcc, 0x4000, v12
	v_fmac_f32_e32 v18, v244, v8
	s_nop 0
	v_addc_co_u32_e32 v53, vcc, 0, v13, vcc
	v_cvt_pk_bf16_f32 v8, v18, s0
	s_and_b64 vcc, exec, s[46:47]
	global_store_short v[52:53], v8, off
	s_cbranch_vccnz .LBB0_748
	v_add_co_u32_e32 v52, vcc, 0x8000, v20
	s_nop 1
	v_addc_co_u32_e32 v53, vcc, 0, v21, vcc
	global_store_dword v[52:53], v18, off
.LBB0_748:
	v_lshlrev_b32_e32 v18, 16, v105
	v_mul_f32_e32 v9, v9, v50
	v_add_co_u32_e32 v50, vcc, 0x4000, v12
	v_fmac_f32_e32 v18, v244, v9
	s_nop 0
	v_addc_co_u32_e32 v51, vcc, 0, v13, vcc
	v_cvt_pk_bf16_f32 v9, v18, s0
	s_and_b64 vcc, exec, s[46:47]
	global_store_short v[50:51], v9, off offset:2048
	s_cbranch_vccnz .LBB0_750
	v_add_co_u32_e32 v50, vcc, 0x9000, v20
	s_nop 1
	v_addc_co_u32_e32 v51, vcc, 0, v21, vcc
	global_store_dword v[50:51], v18, off
.LBB0_750:
	v_lshlrev_b32_e32 v18, 16, v104
	v_mul_f32_e32 v10, v10, v49
	v_add_co_u32_e32 v50, vcc, 0x5000, v12
	v_fmac_f32_e32 v18, v244, v10
	s_nop 0
	v_addc_co_u32_e32 v51, vcc, 0, v13, vcc
	v_cvt_pk_bf16_f32 v10, v18, s0
	s_and_b64 vcc, exec, s[46:47]
	global_store_short v[50:51], v10, off
	s_cbranch_vccnz .LBB0_752
	v_add_co_u32_e32 v50, vcc, 0xa000, v20
	s_nop 1
	v_addc_co_u32_e32 v51, vcc, 0, v21, vcc
	global_store_dword v[50:51], v18, off
.LBB0_752:
	v_lshlrev_b32_e32 v18, 16, v103
	v_mul_f32_e32 v11, v11, v48
	v_add_co_u32_e32 v48, vcc, 0x5000, v12
	v_fmac_f32_e32 v18, v244, v11
	s_nop 0
	v_addc_co_u32_e32 v49, vcc, 0, v13, vcc
	v_cvt_pk_bf16_f32 v11, v18, s0
	s_and_b64 vcc, exec, s[46:47]
	global_store_short v[48:49], v11, off offset:2048
	s_cbranch_vccnz .LBB0_754
	v_add_co_u32_e32 v48, vcc, 0xb000, v20
	s_nop 1
	v_addc_co_u32_e32 v49, vcc, 0, v21, vcc
	global_store_dword v[48:49], v18, off
.LBB0_754:
	v_lshlrev_b32_e32 v18, 16, v102
	v_mul_f32_e32 v4, v4, v43
	v_add_co_u32_e32 v48, vcc, 0x8000, v12
	v_fmac_f32_e32 v18, v244, v4
	s_nop 0
	v_addc_co_u32_e32 v49, vcc, 0, v13, vcc
	v_cvt_pk_bf16_f32 v4, v18, s0
	s_and_b64 vcc, exec, s[46:47]
	global_store_short v[48:49], v4, off
	s_cbranch_vccnz .LBB0_756
	v_add_co_u32_e32 v48, vcc, 0x10000, v20
	s_nop 1
	v_addc_co_u32_e32 v49, vcc, 0, v21, vcc
	global_store_dword v[48:49], v18, off
.LBB0_756:
	v_lshlrev_b32_e32 v18, 16, v101
	v_mul_f32_e32 v5, v5, v42
	v_add_co_u32_e32 v42, vcc, 0x8000, v12
	v_fmac_f32_e32 v18, v244, v5
	s_nop 0
	v_addc_co_u32_e32 v43, vcc, 0, v13, vcc
	v_cvt_pk_bf16_f32 v5, v18, s0
	s_and_b64 vcc, exec, s[46:47]
	global_store_short v[42:43], v5, off offset:2048
	s_cbranch_vccnz .LBB0_758
	v_add_co_u32_e32 v42, vcc, 0x11000, v20
	s_nop 1
	v_addc_co_u32_e32 v43, vcc, 0, v21, vcc
	global_store_dword v[42:43], v18, off
.LBB0_758:
	v_lshlrev_b32_e32 v18, 16, v100
	v_mul_f32_e32 v6, v6, v41
	v_add_co_u32_e32 v42, vcc, 0x9000, v12
	v_fmac_f32_e32 v18, v244, v6
	s_nop 0
	v_addc_co_u32_e32 v43, vcc, 0, v13, vcc
	v_cvt_pk_bf16_f32 v6, v18, s0
	s_and_b64 vcc, exec, s[46:47]
	global_store_short v[42:43], v6, off
	s_cbranch_vccnz .LBB0_760
	v_add_co_u32_e32 v42, vcc, 0x12000, v20
	s_nop 1
	v_addc_co_u32_e32 v43, vcc, 0, v21, vcc
	global_store_dword v[42:43], v18, off
.LBB0_760:
	v_lshlrev_b32_e32 v18, 16, v99
	v_mul_f32_e32 v7, v7, v40
	v_add_co_u32_e32 v40, vcc, 0x9000, v12
	v_fmac_f32_e32 v18, v244, v7
	s_nop 0
	v_addc_co_u32_e32 v41, vcc, 0, v13, vcc
	v_cvt_pk_bf16_f32 v7, v18, s0
	s_and_b64 vcc, exec, s[46:47]
	global_store_short v[40:41], v7, off offset:2048
	s_cbranch_vccnz .LBB0_762
	v_add_co_u32_e32 v40, vcc, 0x13000, v20
	s_nop 1
	v_addc_co_u32_e32 v41, vcc, 0, v21, vcc
	global_store_dword v[40:41], v18, off
.LBB0_762:
	v_lshlrev_b32_e32 v18, 16, v98
	v_mul_f32_e32 v0, v0, v39
	v_add_co_u32_e32 v40, vcc, 0xc000, v12
	v_fmac_f32_e32 v18, v244, v0
	s_nop 0
	v_addc_co_u32_e32 v41, vcc, 0, v13, vcc
	v_cvt_pk_bf16_f32 v0, v18, s0
	s_and_b64 vcc, exec, s[46:47]
	global_store_short v[40:41], v0, off
	s_cbranch_vccnz .LBB0_764
	v_add_co_u32_e32 v40, vcc, 0x18000, v20
	s_nop 1
	v_addc_co_u32_e32 v41, vcc, 0, v21, vcc
	global_store_dword v[40:41], v18, off
.LBB0_764:
	v_lshlrev_b32_e32 v18, 16, v97
	v_mul_f32_e32 v1, v1, v38
	v_add_co_u32_e32 v38, vcc, 0xc000, v12
	v_fmac_f32_e32 v18, v244, v1
	s_nop 0
	v_addc_co_u32_e32 v39, vcc, 0, v13, vcc
	v_cvt_pk_bf16_f32 v1, v18, s0
	s_and_b64 vcc, exec, s[46:47]
	global_store_short v[38:39], v1, off offset:2048
	s_cbranch_vccnz .LBB0_766
	v_add_co_u32_e32 v38, vcc, 0x19000, v20
	s_nop 1
	v_addc_co_u32_e32 v39, vcc, 0, v21, vcc
	global_store_dword v[38:39], v18, off
.LBB0_766:
	v_lshlrev_b32_e32 v18, 16, v95
	v_mul_f32_e32 v2, v2, v37
	v_add_co_u32_e32 v38, vcc, 0xd000, v12
	v_fmac_f32_e32 v18, v244, v2
	s_nop 0
	v_addc_co_u32_e32 v39, vcc, 0, v13, vcc
	v_cvt_pk_bf16_f32 v2, v18, s0
	s_and_b64 vcc, exec, s[46:47]
	global_store_short v[38:39], v2, off
	s_cbranch_vccnz .LBB0_768
	v_add_co_u32_e32 v38, vcc, 0x1a000, v20
	s_nop 1
	v_addc_co_u32_e32 v39, vcc, 0, v21, vcc
	global_store_dword v[38:39], v18, off
.LBB0_768:
	v_lshlrev_b32_e32 v18, 16, v96
	v_mul_f32_e32 v3, v3, v36
	v_add_co_u32_e32 v12, vcc, 0xd000, v12
	v_fmac_f32_e32 v18, v244, v3
	s_nop 0
	v_addc_co_u32_e32 v13, vcc, 0, v13, vcc
	v_cvt_pk_bf16_f32 v3, v18, s0
	s_and_b64 vcc, exec, s[46:47]
	global_store_short v[12:13], v3, off offset:2048
	s_cbranch_vccnz .LBB0_770
	v_add_co_u32_e32 v12, vcc, 0x1b000, v20
	s_nop 1
	v_addc_co_u32_e32 v13, vcc, 0, v21, vcc
	global_store_dword v[12:13], v18, off
